# GEMM tile loops: vmcnt(0) store drain at the tile top moved in front of the loop
# baseline (speedup 1.0000x reference)
.LBB0_204:
	s_or_b64 exec, exec, s[0:1]
	s_add_i32 s2, s2, s3
	s_add_i32 s29, s29, s30
	s_xor_b64 s[12:13], s[12:13], s[14:15]
	s_cmpk_gt_i32 s2, 0xdb
	s_cbranch_scc1 .LBB0_467
	s_waitcnt vmcnt(0)
.LBB0_205:
	s_mul_hi_i32 s0, s2, 0x2e8ba2e9
	s_lshr_b32 s1, s0, 31
	s_ashr_i32 s0, s0, 3
	s_add_i32 s6, s0, s1
	s_lshl_b32 s4, s6, 1
	s_and_b32 s1, s2, 1
	s_add_i32 s7, s4, s26
	s_or_b32 s1, s7, s1
	s_lshl_b32 s4, s1, 8
	s_mul_i32 s0, s6, 0xffffffd4
	v_add_u32_e32 v0, s4, v145
	s_add_i32 s0, s0, s2
	v_ashrrev_i32_e32 v1, 31, v0
	v_lshlrev_b64 v[0:1], 11, v[0:1]
	s_lshl_b32 s48, s0, 6
	s_mov_b32 m0, s27
	v_lshl_add_u64 v[0:1], v[132:133], 0, v[0:1]
	s_and_b32 s5, s48, 0xffffff80
	v_add_u32_e32 v2, s5, v146
	global_load_lds_dwordx4 v[0:1], off
	v_lshl_add_u64 v[4:5], v[0:1], 0, s[16:17]
	s_mov_b32 m0, s31
	s_mov_b64 s[0:1], 0x10000
	v_ashrrev_i32_e32 v3, 31, v2
	global_load_lds_dwordx4 v[4:5], off
	v_lshl_add_u64 v[4:5], v[0:1], 0, s[0:1]
	s_mov_b32 m0, s33
	s_mov_b64 s[0:1], 0x18000
	v_lshlrev_b64 v[2:3], 11, v[2:3]
	global_load_lds_dwordx4 v[4:5], off
	v_lshl_add_u64 v[4:5], v[0:1], 0, s[0:1]
	s_mov_b32 m0, s34
	v_lshl_add_u64 v[2:3], v[134:135], 0, v[2:3]
	global_load_lds_dwordx4 v[4:5], off
	s_mov_b32 m0, s35
	v_lshl_add_u64 v[4:5], v[2:3], 0, s[16:17]
	global_load_lds_dwordx4 v[2:3], off
	s_mov_b32 m0, s36
	s_mov_b64 s[0:1], 0x10040
	global_load_lds_dwordx4 v[4:5], off
	v_lshl_add_u64 v[4:5], v[0:1], 0, 64
	s_mov_b32 m0, s37
	s_mulk_i32 s6, 0xb00
	global_load_lds_dwordx4 v[4:5], off
	v_lshl_add_u64 v[4:5], v[0:1], 0, s[18:19]
	s_mov_b32 m0, s38
	v_cndmask_b32_e64 v6, 0, 1, s[12:13]
	global_load_lds_dwordx4 v[4:5], off
	v_lshl_add_u64 v[4:5], v[0:1], 0, s[0:1]
	s_mov_b32 m0, s39
	s_mov_b64 s[0:1], 0x18040
	global_load_lds_dwordx4 v[4:5], off
	v_lshl_add_u64 v[0:1], v[0:1], 0, s[0:1]
	s_mov_b32 m0, s40
	s_sub_i32 s0, s29, s6
	global_load_lds_dwordx4 v[0:1], off
	v_lshl_add_u64 v[0:1], v[2:3], 0, 64
	s_mov_b32 m0, s41
	s_and_b32 s0, s0, 0xffffff80
	global_load_lds_dwordx4 v[0:1], off
	v_lshl_add_u64 v[0:1], v[2:3], 0, s[18:19]
	s_mov_b32 m0, s42
	s_mov_b32 s6, 2
	global_load_lds_dwordx4 v[0:1], off
	v_add_u32_e32 v0, s0, v146
	v_ashrrev_i32_e32 v1, 31, v0
	v_lshlrev_b64 v[0:1], 11, v[0:1]
	v_lshl_add_u64 v[138:139], v[134:135], 0, v[0:1]
	v_add_u32_e32 v0, s7, v6
	v_lshl_add_u32 v0, v0, 8, v145
	v_ashrrev_i32_e32 v1, 31, v0
	v_lshlrev_b64 v[0:1], 11, v[0:1]
	v_lshl_add_u64 v[140:141], v[132:133], 0, v[0:1]
	s_mov_b64 s[0:1], 0
	s_mov_b32 s7, 0
	v_mov_b32_e32 v0, 0
	v_mov_b32_e32 v1, v131
	v_mov_b32_e32 v2, v131
	v_mov_b32_e32 v3, v131
	v_mov_b32_e32 v4, 0
	v_mov_b32_e32 v5, v131
	v_mov_b32_e32 v6, v131
	v_mov_b32_e32 v7, v131
	v_mov_b32_e32 v8, 0
	v_mov_b32_e32 v9, v131
	v_mov_b32_e32 v10, v131
	v_mov_b32_e32 v11, v131
	v_mov_b32_e32 v12, 0
	v_mov_b32_e32 v13, v131
	v_mov_b32_e32 v14, v131
	v_mov_b32_e32 v15, v131
	v_mov_b32_e32 v16, 0
	v_mov_b32_e32 v17, v131
	v_mov_b32_e32 v18, v131
	v_mov_b32_e32 v19, v131
	v_mov_b32_e32 v20, 0
	v_mov_b32_e32 v21, v131
	v_mov_b32_e32 v22, v131
	v_mov_b32_e32 v23, v131
	v_mov_b32_e32 v24, 0
	v_mov_b32_e32 v25, v131
	v_mov_b32_e32 v26, v131
	v_mov_b32_e32 v27, v131
	v_mov_b32_e32 v28, 0
	v_mov_b32_e32 v29, v131
	v_mov_b32_e32 v30, v131
	v_mov_b32_e32 v31, v131
	v_mov_b32_e32 v32, 0
	v_mov_b32_e32 v33, v131
	v_mov_b32_e32 v34, v131
	v_mov_b32_e32 v35, v131
	v_mov_b32_e32 v36, 0
	v_mov_b32_e32 v37, v131
	v_mov_b32_e32 v38, v131
	v_mov_b32_e32 v39, v131
	v_mov_b32_e32 v44, 0
	v_mov_b32_e32 v45, v131
	v_mov_b32_e32 v46, v131
	v_mov_b32_e32 v47, v131
	v_mov_b32_e32 v52, 0
	v_mov_b32_e32 v53, v131
	v_mov_b32_e32 v54, v131
	v_mov_b32_e32 v55, v131
	v_mov_b32_e32 v60, 0
	v_mov_b32_e32 v61, v131
	v_mov_b32_e32 v62, v131
	v_mov_b32_e32 v63, v131
	v_mov_b32_e32 v68, 0
	v_mov_b32_e32 v69, v131
	v_mov_b32_e32 v70, v131
	v_mov_b32_e32 v71, v131
	v_mov_b32_e32 v76, 0
	v_mov_b32_e32 v77, v131
	v_mov_b32_e32 v78, v131
	v_mov_b32_e32 v79, v131
	v_mov_b32_e32 v84, 0
	v_mov_b32_e32 v85, v131
	v_mov_b32_e32 v86, v131
	v_mov_b32_e32 v87, v131
	v_mov_b32_e32 v40, 0
	v_mov_b32_e32 v41, v131
	v_mov_b32_e32 v42, v131
	v_mov_b32_e32 v43, v131
	v_mov_b32_e32 v48, 0
	v_mov_b32_e32 v49, v131
	v_mov_b32_e32 v50, v131
	v_mov_b32_e32 v51, v131
	v_mov_b32_e32 v56, 0
	v_mov_b32_e32 v57, v131
	v_mov_b32_e32 v58, v131
	v_mov_b32_e32 v59, v131
	v_mov_b32_e32 v64, 0
	v_mov_b32_e32 v65, v131
	v_mov_b32_e32 v66, v131
	v_mov_b32_e32 v67, v131
	v_mov_b32_e32 v72, 0
	v_mov_b32_e32 v73, v131
	v_mov_b32_e32 v74, v131
	v_mov_b32_e32 v75, v131
	v_mov_b32_e32 v80, 0
	v_mov_b32_e32 v81, v131
	v_mov_b32_e32 v82, v131
	v_mov_b32_e32 v83, v131
	v_mov_b32_e32 v88, 0
	v_mov_b32_e32 v89, v131
	v_mov_b32_e32 v90, v131
	v_mov_b32_e32 v91, v131
	v_mov_b32_e32 v92, 0
	v_mov_b32_e32 v93, v131
	v_mov_b32_e32 v94, v131
	v_mov_b32_e32 v95, v131
	v_mov_b32_e32 v96, 0
	v_mov_b32_e32 v97, v131
	v_mov_b32_e32 v98, v131
	v_mov_b32_e32 v99, v131
	v_mov_b32_e32 v100, 0
	v_mov_b32_e32 v101, v131
	v_mov_b32_e32 v102, v131
	v_mov_b32_e32 v103, v131
	v_mov_b32_e32 v104, 0
	v_mov_b32_e32 v105, v131
	v_mov_b32_e32 v106, v131
	v_mov_b32_e32 v107, v131
	v_mov_b32_e32 v108, 0
	v_mov_b32_e32 v109, v131
	v_mov_b32_e32 v110, v131
	v_mov_b32_e32 v111, v131
	v_mov_b32_e32 v112, 0
	v_mov_b32_e32 v113, v131
	v_mov_b32_e32 v114, v131
	v_mov_b32_e32 v115, v131
	v_mov_b32_e32 v116, 0
	v_mov_b32_e32 v117, v131
	v_mov_b32_e32 v118, v131
	v_mov_b32_e32 v119, v131
	v_mov_b32_e32 v120, 0
	v_mov_b32_e32 v121, v131
	v_mov_b32_e32 v122, v131
	v_mov_b32_e32 v123, v131
	v_mov_b32_e32 v124, 0
	v_mov_b32_e32 v125, v131
	v_mov_b32_e32 v126, v131
	v_mov_b32_e32 v127, v131

.LBB0_632:
	s_or_b64 exec, exec, s[34:35]
	v_readlane_b32 s56, v241, 17
	v_and_b32_sdwa v6, v5, v89 dst_sel:DWORD dst_unused:UNUSED_PAD src0_sel:WORD_1 src1_sel:DWORD
	v_and_b32_sdwa v7, v4, v89 dst_sel:DWORD dst_unused:UNUSED_PAD src0_sel:WORD_1 src1_sel:DWORD
	v_readlane_b32 s58, v241, 19
	v_readlane_b32 s59, v241, 20
	v_add3_u32 v4, v4, v7, s52
	v_add3_u32 v5, v5, v6, s52
	v_mov_b64_e32 v[2:3], s[58:59]
	v_cvt_pk_bf16_f32 v1, v1, v1
	v_cvt_pk_bf16_f32 v0, v0, v0
	v_mad_i64_i32 v[2:3], s[30:31], v58, s51, v[2:3]
	v_and_b32_e32 v1, 0xffff0000, v1
	v_and_b32_e32 v0, 0xffff0000, v0
	s_add_i32 s2, s2, s3
	s_add_i32 s37, s37, s38
	v_lshl_add_u64 v[2:3], v[78:79], 1, v[2:3]
	v_or_b32_sdwa v1, v1, v5 dst_sel:DWORD dst_unused:UNUSED_PAD src0_sel:DWORD src1_sel:WORD_1
	v_or_b32_sdwa v0, v0, v4 dst_sel:DWORD dst_unused:UNUSED_PAD src0_sel:DWORD src1_sel:WORD_1
	s_cmpk_lt_i32 s2, 0xc8
	v_readlane_b32 s57, v241, 18
	v_readlane_b32 s60, v241, 21
	v_readlane_b32 s61, v241, 22
	v_readlane_b32 s62, v241, 23
	v_readlane_b32 s63, v241, 24
	global_store_dwordx2 v[2:3], v[0:1], off offset:96
	s_cbranch_scc0 .LBB0_689
	s_waitcnt vmcnt(0)
.LBB0_633:
	s_mul_hi_i32 s30, s2, 0x66666667
	s_lshr_b32 s31, s30, 31
	s_ashr_i32 s30, s30, 4
	s_add_i32 s30, s30, s31
	s_lshl_b32 s34, s30, 2
	s_and_b32 s31, s2, 3
	s_add_i32 s34, s34, s33
	s_or_b32 s31, s34, s31
	s_lshl_b32 s54, s31, 7
	s_mulk_i32 s30, 0xfb00
	v_add_u32_e32 v0, s54, v80
	s_add_i32 s53, s37, s30
	v_ashrrev_i32_e32 v1, 31, v0
	s_and_b32 s30, s53, 0xffffff80
	v_add_u32_e32 v2, s30, v80
	v_lshlrev_b64 v[0:1], 9, v[0:1]
	s_mov_b32 m0, s36
	v_ashrrev_i32_e32 v3, 31, v2
	v_lshl_add_u64 v[78:79], v[74:75], 0, v[0:1]
	v_lshlrev_b64 v[2:3], 9, v[2:3]
	global_load_lds_dwordx4 v[78:79], off
	v_lshl_add_u64 v[0:1], v[78:79], 0, s[0:1]
	s_mov_b32 m0, s39
	v_lshl_add_u64 v[68:69], v[72:73], 0, v[2:3]
	global_load_lds_dwordx4 v[0:1], off
	s_mov_b32 m0, s40
	v_lshl_add_u64 v[0:1], v[68:69], 0, s[0:1]
	global_load_lds_dwordx4 v[68:69], off
	s_mov_b32 m0, s41
	v_lshl_add_u64 v[4:5], v[78:79], 0, s[8:9]
	global_load_lds_dwordx4 v[0:1], off
	v_lshl_add_u64 v[0:1], v[78:79], 0, 64
	s_mov_b32 m0, s42
	v_lshl_add_u64 v[6:7], v[78:79], 0, s[6:7]
	global_load_lds_dwordx4 v[0:1], off
	v_lshl_add_u64 v[0:1], v[78:79], 0, s[4:5]
	s_mov_b32 m0, s43
	v_lshl_add_u64 v[2:3], v[68:69], 0, s[8:9]
	global_load_lds_dwordx4 v[0:1], off
	v_lshl_add_u64 v[0:1], v[68:69], 0, 64
	s_mov_b32 m0, s44
	v_lshl_add_u64 v[90:91], v[78:79], 0, s[12:13]
	global_load_lds_dwordx4 v[0:1], off
	v_lshl_add_u64 v[0:1], v[68:69], 0, s[4:5]
	s_mov_b32 m0, s45
	v_lshl_add_u64 v[92:93], v[78:79], 0, s[10:11]
	global_load_lds_dwordx4 v[0:1], off
	s_waitcnt vmcnt(4)
	s_waitcnt lgkmcnt(0)
	s_barrier
	s_mov_b32 m0, s46
	v_lshl_add_u64 v[0:1], v[68:69], 0, s[6:7]
	global_load_lds_dwordx4 v[4:5], off
	s_mov_b32 m0, s47
	s_nop 0
	global_load_lds_dwordx4 v[6:7], off
	s_mov_b32 m0, s48
	s_nop 0
	global_load_lds_dwordx4 v[2:3], off
	s_mov_b32 m0, s49
	s_nop 0
	global_load_lds_dwordx4 v[0:1], off
	ds_read_b128 v[0:3], v82
	ds_read_b128 v[4:7], v82 offset:1024
	ds_read_b128 v[8:11], v82 offset:2048
	ds_read_b128 v[12:15], v82 offset:3072
	ds_read_b128 v[16:19], v83
	ds_read_b128 v[20:23], v83 offset:1024
	ds_read_b128 v[24:27], v83 offset:2048
	ds_read_b128 v[28:31], v83 offset:3072
	s_waitcnt lgkmcnt(0)
	s_waitcnt vmcnt(4)
	s_waitcnt lgkmcnt(0)
	s_barrier
	s_mov_b32 m0, s36
	v_mfma_f32_16x16x32_bf16 v[32:35], v[16:19], v[0:3], 0
	global_load_lds_dwordx4 v[90:91], off
	s_mov_b32 m0, s39
	v_mfma_f32_16x16x32_bf16 v[36:39], v[20:23], v[0:3], 0
	global_load_lds_dwordx4 v[92:93], off
	s_mov_b32 m0, s40
	v_mfma_f32_16x16x32_bf16 v[40:43], v[24:27], v[0:3], 0
	v_mfma_f32_16x16x32_bf16 v[0:3], v[28:31], v[0:3], 0
	v_mfma_f32_16x16x32_bf16 v[44:47], v[16:19], v[4:7], 0
	v_mfma_f32_16x16x32_bf16 v[48:51], v[20:23], v[4:7], 0
	v_mfma_f32_16x16x32_bf16 v[52:55], v[24:27], v[4:7], 0
	v_mfma_f32_16x16x32_bf16 v[4:7], v[28:31], v[4:7], 0
	v_mfma_f32_16x16x32_bf16 v[56:59], v[16:19], v[8:11], 0
	v_mfma_f32_16x16x32_bf16 v[60:63], v[20:23], v[8:11], 0
	v_mfma_f32_16x16x32_bf16 v[64:67], v[24:27], v[8:11], 0
	v_mfma_f32_16x16x32_bf16 v[8:11], v[28:31], v[8:11], 0
	v_mfma_f32_16x16x32_bf16 v[16:19], v[16:19], v[12:15], 0
	v_mfma_f32_16x16x32_bf16 v[20:23], v[20:23], v[12:15], 0
	v_mfma_f32_16x16x32_bf16 v[24:27], v[24:27], v[12:15], 0
	v_mfma_f32_16x16x32_bf16 v[12:15], v[28:31], v[12:15], 0
	v_lshl_add_u64 v[30:31], v[68:69], 0, s[12:13]
	v_lshl_add_u64 v[28:29], v[68:69], 0, s[10:11]
	global_load_lds_dwordx4 v[30:31], off
	s_mov_b32 m0, s41
	s_nop 0
	global_load_lds_dwordx4 v[28:29], off
	ds_read_b128 v[28:31], v85
	ds_read_b128 v[90:93], v85 offset:1024
	ds_read_b128 v[94:97], v85 offset:2048
	ds_read_b128 v[98:101], v85 offset:3072
	ds_read_b128 v[102:105], v86
	ds_read_b128 v[106:109], v86 offset:1024
	ds_read_b128 v[110:113], v86 offset:2048
	ds_read_b128 v[114:117], v86 offset:3072
	s_waitcnt lgkmcnt(0)
	s_waitcnt vmcnt(4)
	s_waitcnt lgkmcnt(0)
	s_barrier
	v_mfma_f32_16x16x32_bf16 v[32:35], v[102:105], v[28:31], v[32:35]
	s_mov_b32 m0, s42
	v_mfma_f32_16x16x32_bf16 v[36:39], v[106:109], v[28:31], v[36:39]
	v_mfma_f32_16x16x32_bf16 v[40:43], v[110:113], v[28:31], v[40:43]
	v_mfma_f32_16x16x32_bf16 v[0:3], v[114:117], v[28:31], v[0:3]
	v_mfma_f32_16x16x32_bf16 v[28:31], v[102:105], v[90:93], v[44:47]
	v_mfma_f32_16x16x32_bf16 v[44:47], v[106:109], v[90:93], v[48:51]
	v_mfma_f32_16x16x32_bf16 v[48:51], v[110:113], v[90:93], v[52:55]
	v_mfma_f32_16x16x32_bf16 v[4:7], v[114:117], v[90:93], v[4:7]
	v_lshl_add_u64 v[90:91], v[78:79], 0, s[16:17]
	v_lshl_add_u64 v[92:93], v[78:79], 0, s[14:15]
	global_load_lds_dwordx4 v[90:91], off
	s_mov_b32 m0, s43
	v_mfma_f32_16x16x32_bf16 v[52:55], v[102:105], v[94:97], v[56:59]
	global_load_lds_dwordx4 v[92:93], off
	s_mov_b32 m0, s44
	v_mfma_f32_16x16x32_bf16 v[56:59], v[106:109], v[94:97], v[60:63]
	v_mfma_f32_16x16x32_bf16 v[60:63], v[110:113], v[94:97], v[64:67]
	s_nop 2
	v_lshl_add_u64 v[66:67], v[68:69], 0, s[16:17]
	v_lshl_add_u64 v[64:65], v[68:69], 0, s[14:15]
	global_load_lds_dwordx4 v[66:67], off
	s_mov_b32 m0, s45
	v_mfma_f32_16x16x32_bf16 v[8:11], v[114:117], v[94:97], v[8:11]
	global_load_lds_dwordx4 v[64:65], off
	s_mov_b32 m0, s46
	v_mfma_f32_16x16x32_bf16 v[16:19], v[102:105], v[98:101], v[16:19]
	v_mfma_f32_16x16x32_bf16 v[20:23], v[106:109], v[98:101], v[20:23]
	v_mfma_f32_16x16x32_bf16 v[24:27], v[110:113], v[98:101], v[24:27]
	v_mfma_f32_16x16x32_bf16 v[12:15], v[114:117], v[98:101], v[12:15]
	ds_read_b128 v[64:67], v87
	ds_read_b128 v[90:93], v87 offset:1024
	ds_read_b128 v[94:97], v87 offset:2048
	ds_read_b128 v[98:101], v87 offset:3072
	ds_read_b128 v[102:105], v88
	ds_read_b128 v[106:109], v88 offset:1024
	ds_read_b128 v[110:113], v88 offset:2048
	ds_read_b128 v[114:117], v88 offset:3072
	s_waitcnt lgkmcnt(0)
	s_waitcnt vmcnt(4)
	s_waitcnt lgkmcnt(0)
	s_barrier
	v_mfma_f32_16x16x32_bf16 v[28:31], v[102:105], v[90:93], v[28:31]
	v_mfma_f32_16x16x32_bf16 v[44:47], v[106:109], v[90:93], v[44:47]
	v_mfma_f32_16x16x32_bf16 v[48:51], v[110:113], v[90:93], v[48:51]
	v_mfma_f32_16x16x32_bf16 v[4:7], v[114:117], v[90:93], v[4:7]
	v_lshl_add_u64 v[90:91], v[78:79], 0, s[20:21]
	v_lshl_add_u64 v[92:93], v[78:79], 0, s[18:19]
	global_load_lds_dwordx4 v[90:91], off
	s_mov_b32 m0, s47
	v_mfma_f32_16x16x32_bf16 v[32:35], v[102:105], v[64:67], v[32:35]
	global_load_lds_dwordx4 v[92:93], off
	s_mov_b32 m0, s48
	v_mfma_f32_16x16x32_bf16 v[36:39], v[106:109], v[64:67], v[36:39]
	v_mfma_f32_16x16x32_bf16 v[40:43], v[110:113], v[64:67], v[40:43]
	v_mfma_f32_16x16x32_bf16 v[0:3], v[114:117], v[64:67], v[0:3]
	v_lshl_add_u64 v[66:67], v[68:69], 0, s[20:21]
	v_lshl_add_u64 v[64:65], v[68:69], 0, s[18:19]
	global_load_lds_dwordx4 v[66:67], off
	s_mov_b32 m0, s49
	v_mfma_f32_16x16x32_bf16 v[52:55], v[102:105], v[94:97], v[52:55]
	global_load_lds_dwordx4 v[64:65], off
	s_mov_b32 m0, s36
	v_mfma_f32_16x16x32_bf16 v[56:59], v[106:109], v[94:97], v[56:59]
	v_mfma_f32_16x16x32_bf16 v[60:63], v[110:113], v[94:97], v[60:63]
	v_mfma_f32_16x16x32_bf16 v[8:11], v[114:117], v[94:97], v[8:11]
	v_mfma_f32_16x16x32_bf16 v[16:19], v[102:105], v[98:101], v[16:19]
	v_mfma_f32_16x16x32_bf16 v[20:23], v[106:109], v[98:101], v[20:23]
	v_mfma_f32_16x16x32_bf16 v[24:27], v[110:113], v[98:101], v[24:27]
	v_mfma_f32_16x16x32_bf16 v[12:15], v[114:117], v[98:101], v[12:15]
	ds_read_b128 v[64:67], v82
	ds_read_b128 v[90:93], v82 offset:1024
	ds_read_b128 v[94:97], v82 offset:2048
	ds_read_b128 v[98:101], v82 offset:3072
	ds_read_b128 v[102:105], v83
	ds_read_b128 v[106:109], v83 offset:1024
	ds_read_b128 v[110:113], v83 offset:2048
	ds_read_b128 v[114:117], v83 offset:3072
	s_waitcnt lgkmcnt(0)
	s_waitcnt vmcnt(4)
	s_waitcnt lgkmcnt(0)
	s_barrier
	v_mfma_f32_16x16x32_bf16 v[28:31], v[102:105], v[90:93], v[28:31]
	v_mfma_f32_16x16x32_bf16 v[44:47], v[106:109], v[90:93], v[44:47]
	v_mfma_f32_16x16x32_bf16 v[48:51], v[110:113], v[90:93], v[48:51]
	v_mfma_f32_16x16x32_bf16 v[4:7], v[114:117], v[90:93], v[4:7]
	v_lshl_add_u64 v[90:91], v[78:79], 0, s[24:25]
	v_lshl_add_u64 v[92:93], v[78:79], 0, s[22:23]
	global_load_lds_dwordx4 v[90:91], off
	s_mov_b32 m0, s39
	v_mfma_f32_16x16x32_bf16 v[32:35], v[102:105], v[64:67], v[32:35]
	global_load_lds_dwordx4 v[92:93], off
	s_mov_b32 m0, s40
	v_mfma_f32_16x16x32_bf16 v[36:39], v[106:109], v[64:67], v[36:39]
	v_mfma_f32_16x16x32_bf16 v[40:43], v[110:113], v[64:67], v[40:43]
	v_mfma_f32_16x16x32_bf16 v[0:3], v[114:117], v[64:67], v[0:3]
	v_lshl_add_u64 v[66:67], v[68:69], 0, s[24:25]
	v_lshl_add_u64 v[64:65], v[68:69], 0, s[22:23]
	global_load_lds_dwordx4 v[66:67], off
	s_mov_b32 m0, s41
	v_mfma_f32_16x16x32_bf16 v[52:55], v[102:105], v[94:97], v[52:55]
	global_load_lds_dwordx4 v[64:65], off
	s_mov_b32 m0, s42
	v_mfma_f32_16x16x32_bf16 v[56:59], v[106:109], v[94:97], v[56:59]
	v_mfma_f32_16x16x32_bf16 v[60:63], v[110:113], v[94:97], v[60:63]
	v_mfma_f32_16x16x32_bf16 v[8:11], v[114:117], v[94:97], v[8:11]
	v_mfma_f32_16x16x32_bf16 v[16:19], v[102:105], v[98:101], v[16:19]
	v_mfma_f32_16x16x32_bf16 v[20:23], v[106:109], v[98:101], v[20:23]
	v_mfma_f32_16x16x32_bf16 v[24:27], v[110:113], v[98:101], v[24:27]
	v_mfma_f32_16x16x32_bf16 v[12:15], v[114:117], v[98:101], v[12:15]
	ds_read_b128 v[64:67], v85
	ds_read_b128 v[90:93], v85 offset:1024
	ds_read_b128 v[94:97], v85 offset:2048
	ds_read_b128 v[98:101], v85 offset:3072
	ds_read_b128 v[102:105], v86
	ds_read_b128 v[106:109], v86 offset:1024
	ds_read_b128 v[110:113], v86 offset:2048
	ds_read_b128 v[114:117], v86 offset:3072
	s_waitcnt lgkmcnt(0)
	s_waitcnt vmcnt(4)
	s_waitcnt lgkmcnt(0)
	s_barrier
	v_mfma_f32_16x16x32_bf16 v[32:35], v[102:105], v[64:67], v[32:35]
	v_mfma_f32_16x16x32_bf16 v[36:39], v[106:109], v[64:67], v[36:39]
	v_mfma_f32_16x16x32_bf16 v[40:43], v[110:113], v[64:67], v[40:43]
	v_mfma_f32_16x16x32_bf16 v[0:3], v[114:117], v[64:67], v[0:3]
	v_lshl_add_u64 v[64:65], v[68:69], 0, s[26:27]
	v_lshl_add_u64 v[66:67], v[68:69], 0, s[28:29]
	v_lshl_add_u64 v[68:69], v[78:79], 0, s[28:29]
	v_lshl_add_u64 v[78:79], v[78:79], 0, s[26:27]
	global_load_lds_dwordx4 v[68:69], off
	s_mov_b32 m0, s43
	v_mfma_f32_16x16x32_bf16 v[28:31], v[102:105], v[90:93], v[28:31]
	global_load_lds_dwordx4 v[78:79], off
	s_mov_b32 m0, s44
	v_mfma_f32_16x16x32_bf16 v[44:47], v[106:109], v[90:93], v[44:47]
	global_load_lds_dwordx4 v[66:67], off
	s_mov_b32 m0, s45
	v_mfma_f32_16x16x32_bf16 v[48:51], v[110:113], v[90:93], v[48:51]
	global_load_lds_dwordx4 v[64:65], off
	v_or_b32_e32 v78, s30, v84
	v_mfma_f32_16x16x32_bf16 v[4:7], v[114:117], v[90:93], v[4:7]
	v_cmp_lt_i32_e32 vcc, s50, v78
	v_mfma_f32_16x16x32_bf16 v[52:55], v[102:105], v[94:97], v[52:55]
	v_mfma_f32_16x16x32_bf16 v[56:59], v[106:109], v[94:97], v[56:59]
	v_mfma_f32_16x16x32_bf16 v[60:63], v[110:113], v[94:97], v[60:63]
	v_mfma_f32_16x16x32_bf16 v[8:11], v[114:117], v[94:97], v[8:11]
	v_mfma_f32_16x16x32_bf16 v[16:19], v[102:105], v[98:101], v[16:19]
	v_mfma_f32_16x16x32_bf16 v[20:23], v[106:109], v[98:101], v[20:23]
	v_mfma_f32_16x16x32_bf16 v[24:27], v[110:113], v[98:101], v[24:27]
	v_mfma_f32_16x16x32_bf16 v[12:15], v[114:117], v[98:101], v[12:15]
	ds_read_b128 v[64:67], v87
	ds_read_b128 v[90:93], v87 offset:1024
	ds_read_b128 v[94:97], v87 offset:2048
	ds_read_b128 v[98:101], v87 offset:3072
	ds_read_b128 v[102:105], v88
	ds_read_b128 v[106:109], v88 offset:1024
	ds_read_b128 v[110:113], v88 offset:2048
	ds_read_b128 v[114:117], v88 offset:3072
	s_waitcnt lgkmcnt(0)
	s_waitcnt vmcnt(4)
	s_waitcnt lgkmcnt(0)
	s_barrier
	v_mfma_f32_16x16x32_bf16 v[32:35], v[102:105], v[64:67], v[32:35]
	v_mfma_f32_16x16x32_bf16 v[36:39], v[106:109], v[64:67], v[36:39]
	v_mfma_f32_16x16x32_bf16 v[40:43], v[110:113], v[64:67], v[40:43]
	v_mfma_f32_16x16x32_bf16 v[0:3], v[114:117], v[64:67], v[0:3]
	v_mfma_f32_16x16x32_bf16 v[28:31], v[102:105], v[90:93], v[28:31]
	v_mfma_f32_16x16x32_bf16 v[44:47], v[106:109], v[90:93], v[44:47]
	v_mfma_f32_16x16x32_bf16 v[48:51], v[110:113], v[90:93], v[48:51]
	v_mfma_f32_16x16x32_bf16 v[4:7], v[114:117], v[90:93], v[4:7]
	v_mfma_f32_16x16x32_bf16 v[52:55], v[102:105], v[94:97], v[52:55]
	v_mfma_f32_16x16x32_bf16 v[56:59], v[106:109], v[94:97], v[56:59]
	v_mfma_f32_16x16x32_bf16 v[60:63], v[110:113], v[94:97], v[60:63]
	v_mfma_f32_16x16x32_bf16 v[8:11], v[114:117], v[94:97], v[8:11]
	v_mfma_f32_16x16x32_bf16 v[16:19], v[102:105], v[98:101], v[16:19]
	v_mfma_f32_16x16x32_bf16 v[20:23], v[106:109], v[98:101], v[20:23]
	v_mfma_f32_16x16x32_bf16 v[24:27], v[110:113], v[98:101], v[24:27]
	v_mfma_f32_16x16x32_bf16 v[12:15], v[114:117], v[98:101], v[12:15]
	ds_read_b128 v[64:67], v82
	ds_read_b128 v[90:93], v82 offset:1024
	ds_read_b128 v[94:97], v82 offset:2048
	ds_read_b128 v[98:101], v82 offset:3072
	ds_read_b128 v[102:105], v83
	ds_read_b128 v[106:109], v83 offset:1024
	ds_read_b128 v[110:113], v83 offset:2048
	ds_read_b128 v[114:117], v83 offset:3072
	s_waitcnt lgkmcnt(0)
	s_waitcnt vmcnt(0)
	s_waitcnt lgkmcnt(0)
	s_barrier
	v_mfma_f32_16x16x32_bf16 v[32:35], v[102:105], v[64:67], v[32:35]
	v_mfma_f32_16x16x32_bf16 v[36:39], v[106:109], v[64:67], v[36:39]
	v_mfma_f32_16x16x32_bf16 v[40:43], v[110:113], v[64:67], v[40:43]
	v_mfma_f32_16x16x32_bf16 v[0:3], v[114:117], v[64:67], v[0:3]
	v_mfma_f32_16x16x32_bf16 v[118:121], v[102:105], v[90:93], v[28:31]
	v_mfma_f32_16x16x32_bf16 v[122:125], v[106:109], v[90:93], v[44:47]
	v_mfma_f32_16x16x32_bf16 v[48:51], v[110:113], v[90:93], v[48:51]
	v_mfma_f32_16x16x32_bf16 v[4:7], v[114:117], v[90:93], v[4:7]
	v_mfma_f32_16x16x32_bf16 v[52:55], v[102:105], v[94:97], v[52:55]
	v_mfma_f32_16x16x32_bf16 v[90:93], v[106:109], v[94:97], v[56:59]
	v_mfma_f32_16x16x32_bf16 v[126:129], v[110:113], v[94:97], v[60:63]
	v_mfma_f32_16x16x32_bf16 v[94:97], v[114:117], v[94:97], v[8:11]
	v_mfma_f32_16x16x32_bf16 v[16:19], v[102:105], v[98:101], v[16:19]
	v_mfma_f32_16x16x32_bf16 v[102:105], v[106:109], v[98:101], v[20:23]
	v_mfma_f32_16x16x32_bf16 v[106:109], v[110:113], v[98:101], v[24:27]
	v_mfma_f32_16x16x32_bf16 v[98:101], v[114:117], v[98:101], v[12:15]
	ds_read_b128 v[8:11], v85
	ds_read_b128 v[20:23], v85 offset:1024
	ds_read_b128 v[110:113], v85 offset:2048
	ds_read_b128 v[114:117], v85 offset:3072
	ds_read_b128 v[130:133], v86
	ds_read_b128 v[134:137], v86 offset:1024
	ds_read_b128 v[138:141], v86 offset:2048
	ds_read_b128 v[142:145], v86 offset:3072
	s_waitcnt lgkmcnt(0)
	s_waitcnt lgkmcnt(0)
	s_barrier
	v_mfma_f32_16x16x32_bf16 v[66:69], v[130:133], v[8:11], v[32:35]
	v_mfma_f32_16x16x32_bf16 v[44:47], v[134:137], v[8:11], v[36:39]
	v_mfma_f32_16x16x32_bf16 v[28:31], v[138:141], v[8:11], v[40:43]
	v_mfma_f32_16x16x32_bf16 v[12:15], v[142:145], v[8:11], v[0:3]
	v_mfma_f32_16x16x32_bf16 v[62:65], v[130:133], v[20:23], v[118:121]
	v_mfma_f32_16x16x32_bf16 v[40:43], v[134:137], v[20:23], v[122:125]
	v_mfma_f32_16x16x32_bf16 v[24:27], v[138:141], v[20:23], v[48:51]
	v_mfma_f32_16x16x32_bf16 v[8:11], v[142:145], v[20:23], v[4:7]
	v_mfma_f32_16x16x32_bf16 v[58:61], v[130:133], v[110:113], v[52:55]
	v_mfma_f32_16x16x32_bf16 v[36:39], v[134:137], v[110:113], v[90:93]
	v_mfma_f32_16x16x32_bf16 v[20:23], v[138:141], v[110:113], v[126:129]
	v_mfma_f32_16x16x32_bf16 v[4:7], v[142:145], v[110:113], v[94:97]
	v_mfma_f32_16x16x32_bf16 v[48:51], v[130:133], v[114:117], v[16:19]
	v_mfma_f32_16x16x32_bf16 v[32:35], v[134:137], v[114:117], v[102:105]
	v_mfma_f32_16x16x32_bf16 v[16:19], v[138:141], v[114:117], v[106:109]
	v_mfma_f32_16x16x32_bf16 v[0:3], v[142:145], v[114:117], v[98:101]
	s_and_saveexec_b64 s[34:35], vcc
	s_xor_b64 s[34:35], exec, s[34:35]
	s_cbranch_execz .LBB0_636
	s_cmpk_gt_u32 s53, 0x3ff
	s_cbranch_scc1 .LBB0_649
	v_readlane_b32 s56, v241, 57
	v_mov_b32_e32 v79, v71
	v_readlane_b32 s68, v240, 5
	v_readlane_b32 s69, v240, 6
	v_readlane_b32 s57, v241, 58
	v_readlane_b32 s58, v241, 59
	v_lshl_add_u64 v[52:53], v[78:79], 2, s[68:69]
	global_load_dwordx4 v[54:57], v[52:53], off offset:-2048
	v_readlane_b32 s59, v241, 60
	v_readlane_b32 s60, v241, 61
	v_readlane_b32 s61, v241, 62
	v_readlane_b32 s62, v241, 63
	v_readlane_b32 s63, v240, 0
	v_readlane_b32 s64, v240, 1
	v_readlane_b32 s65, v240, 2
	v_readlane_b32 s66, v240, 3
	v_readlane_b32 s67, v240, 4
	v_readlane_b32 s70, v240, 7
	v_readlane_b32 s71, v240, 8
	s_mov_b64 s[30:31], -1
	s_waitcnt vmcnt(0)
	v_mov_b32_e32 v53, v56
	v_mov_b32_e32 v52, v54
	v_mov_b32_e32 v56, v55

.LBB0_1403:
	s_or_b64 exec, exec, s[0:1]
	s_mov_b32 s0, s74
	s_mov_b32 s1, s76
	s_waitcnt lgkmcnt(0)
	s_barrier
	v_mov_b32_e32 v0, v226
	s_ashr_i32 s2, s0, 3
	s_cmpk_gt_i32 s2, 0x9f
	v_readfirstlane_b32 s4, v0
	s_cbranch_scc1 .LBB0_1408
	s_ashr_i32 s3, s1, 3
	s_ashr_i32 s1, s4, 1
	v_bfe_u32 v1, v0, 2, 4
	s_andn2_b32 s1, s1, 31
	v_or_b32_e32 v85, s1, v1
	v_bfe_u32 v1, v0, 4, 2
	v_lshrrev_b32_e32 v2, 2, v0
	v_bitop3_b32 v2, v1, v2, 3 bitop3:0x78
	v_bitop3_b32 v4, v1, v0, 3 bitop3:0x78
	v_lshlrev_b32_e32 v3, 4, v2
	v_lshlrev_b32_e32 v2, 3, v4
	v_lshlrev_b32_e32 v68, 4, v4
	v_ashrrev_i32_e32 v4, 1, v0
	v_and_b32_e32 v84, 15, v0
	v_and_b32_e32 v86, 0xffffffc0, v4
	s_and_b32 s9, s0, 7
	v_or_b32_e32 v4, v86, v84
	v_and_b32_e32 v87, 64, v0
	v_lshlrev_b32_e32 v0, 6, v0
	s_movk_i32 s0, 0x13c0
	v_readlane_b32 s16, v241, 17
	v_readlane_b32 s36, v241, 1
	v_mov_b32_e32 v69, 0
	s_lshl_b32 s14, s1, 6
	v_lshl_or_b32 v88, v4, 6, v3
	v_and_or_b32 v3, v0, s0, v3
	v_lshlrev_b32_e32 v0, 2, v1
	v_readlane_b32 s17, v241, 18
	v_readlane_b32 s18, v241, 19
	v_readlane_b32 s19, v241, 20
	v_readlane_b32 s20, v241, 21
	v_readlane_b32 s21, v241, 22
	v_readlane_b32 s22, v241, 23
	v_readlane_b32 s23, v241, 24
	v_readlane_b32 s46, v241, 11
	v_readlane_b32 s47, v241, 12
	s_mul_i32 s9, s9, 20
	v_lshl_add_u64 v[70:71], s[88:89], 0, v[68:69]
	v_or_b32_e32 v89, 0x2000, v3
	v_add_u32_e32 v90, 0x4000, v88
	v_or_b32_e32 v91, 0x6000, v3
	v_lshl_add_u64 v[72:73], s[20:21], 0, v[68:69]
	s_lshl_b32 s15, s2, 5
	s_lshl_b32 s16, s3, 5
	s_add_i32 s17, s14, 0x400
	s_add_i32 s18, s14, 0x2000
	s_add_i32 s19, s14, 0x2400
	s_add_i32 s20, s14, 0x4000
	s_add_i32 s21, s14, 0x4400
	s_add_i32 s22, s14, 0x6000
	s_add_i32 s23, s14, 0x6400
	s_mov_b32 s1, 0
	v_lshlrev_b32_e32 v68, 1, v2
	s_mov_b64 s[4:5], 0x80
	s_mov_b64 s[6:7], 0xc0
	v_mov_b64_e32 v[74:75], s[46:47]
	v_lshlrev_b32_e32 v76, 2, v0
	v_mov_b32_e32 v77, v69
	s_mov_b32 s8, 0x3fb504f3
	v_readlane_b32 s37, v241, 2
	v_readlane_b32 s38, v241, 3
	v_readlane_b32 s39, v241, 4
	v_readlane_b32 s40, v241, 5
	v_readlane_b32 s41, v241, 6
	v_readlane_b32 s42, v241, 7
	v_readlane_b32 s43, v241, 8
	v_readlane_b32 s44, v241, 9
	v_readlane_b32 s45, v241, 10
	v_readlane_b32 s48, v241, 13
	v_readlane_b32 s49, v241, 14
	v_readlane_b32 s50, v241, 15
	v_readlane_b32 s51, v241, 16
	s_waitcnt vmcnt(0)
.LBB0_1405:
	s_ashr_i32 s0, s2, 31
	s_lshr_b32 s0, s0, 27
	s_add_i32 s0, s2, s0
	s_ashr_i32 s0, s0, 5
	s_lshl_b32 s10, s0, 2
	s_and_b32 s11, s2, 3
	s_add_i32 s10, s10, s9
	s_or_b32 s10, s10, s11
	s_lshl_b32 s24, s10, 7
	s_lshl_b32 s0, s0, 10
	s_lshl_b32 s10, s2, 5
	s_sub_i32 s10, s10, s0
	v_add_u32_e32 v64, s24, v85
	s_and_b32 s25, s10, 0xffffff80
	s_movk_i32 s10, 0x300
	v_add_u32_e32 v0, s25, v85
	v_mad_i64_i32 v[2:3], s[10:11], v64, s10, v[72:73]
	s_mov_b32 m0, s14
	v_ashrrev_i32_e32 v1, 31, v0
	s_mov_b64 s[10:11], 0x3000
	v_lshlrev_b64 v[0:1], 11, v[0:1]
	global_load_lds_dwordx4 v[2:3], off
	v_lshl_add_u64 v[4:5], v[2:3], 0, s[10:11]
	s_mov_b32 m0, s17
	v_lshl_add_u64 v[0:1], v[70:71], 0, v[0:1]
	global_load_lds_dwordx4 v[4:5], off
	s_mov_b32 m0, s18
	s_mov_b64 s[10:11], 0x8000
	global_load_lds_dwordx4 v[0:1], off
	v_lshl_add_u64 v[4:5], v[0:1], 0, s[10:11]
	s_mov_b32 m0, s19
	s_mov_b64 s[10:11], 0x3040
	global_load_lds_dwordx4 v[4:5], off
	v_lshl_add_u64 v[4:5], v[2:3], 0, 64
	s_mov_b32 m0, s20
	v_lshl_add_u64 v[2:3], v[2:3], 0, s[10:11]
	global_load_lds_dwordx4 v[4:5], off
	s_mov_b32 m0, s21
	s_mov_b64 s[10:11], 0x8040
	global_load_lds_dwordx4 v[2:3], off
	v_lshl_add_u64 v[2:3], v[0:1], 0, 64
	s_mov_b32 m0, s22
	v_lshl_add_u64 v[0:1], v[0:1], 0, s[10:11]
	global_load_lds_dwordx4 v[2:3], off
	s_mov_b32 m0, s23
	s_sub_i32 s0, s15, s0
	global_load_lds_dwordx4 v[0:1], off
	s_and_b32 s0, s0, 0xffffff80
	v_add_u32_e32 v0, s0, v85
	v_ashrrev_i32_e32 v1, 31, v0
	v_lshlrev_b64 v[0:1], 11, v[0:1]
	v_readlane_b32 s36, v241, 17
	v_lshl_add_u64 v[66:67], v[70:71], 0, v[0:1]
	s_mov_b64 s[10:11], 0
	s_mov_b64 s[12:13], 0
	s_mov_b32 s26, s1
	s_mov_b32 s28, 2
	s_mov_b32 s27, s1
	v_mov_b32_e32 v0, 0
	v_mov_b32_e32 v1, v69
	v_mov_b32_e32 v2, v69
	v_mov_b32_e32 v3, v69
	v_mov_b32_e32 v4, 0
	v_mov_b32_e32 v5, v69
	v_mov_b32_e32 v6, v69
	v_mov_b32_e32 v7, v69
	v_mov_b32_e32 v8, 0
	v_mov_b32_e32 v9, v69
	v_mov_b32_e32 v10, v69
	v_mov_b32_e32 v11, v69
	v_mov_b32_e32 v12, 0
	v_mov_b32_e32 v13, v69
	v_mov_b32_e32 v14, v69
	v_mov_b32_e32 v15, v69
	v_mov_b32_e32 v16, 0
	v_mov_b32_e32 v17, v69
	v_mov_b32_e32 v18, v69
	v_mov_b32_e32 v19, v69
	v_mov_b32_e32 v20, 0
	v_mov_b32_e32 v21, v69
	v_mov_b32_e32 v22, v69
	v_mov_b32_e32 v23, v69
	v_mov_b32_e32 v24, 0
	v_mov_b32_e32 v25, v69
	v_mov_b32_e32 v26, v69
	v_mov_b32_e32 v27, v69
	v_mov_b32_e32 v28, 0
	v_mov_b32_e32 v29, v69
	v_mov_b32_e32 v30, v69
	v_mov_b32_e32 v31, v69
	v_mov_b32_e32 v32, 0
	v_mov_b32_e32 v33, v69
	v_mov_b32_e32 v34, v69
	v_mov_b32_e32 v35, v69
	v_mov_b32_e32 v36, 0
	v_mov_b32_e32 v37, v69
	v_mov_b32_e32 v38, v69
	v_mov_b32_e32 v39, v69
	v_mov_b32_e32 v40, 0
	v_mov_b32_e32 v41, v69
	v_mov_b32_e32 v42, v69
	v_mov_b32_e32 v43, v69
	v_mov_b32_e32 v44, 0
	v_mov_b32_e32 v45, v69
	v_mov_b32_e32 v46, v69
	v_mov_b32_e32 v47, v69
	v_mov_b32_e32 v48, 0
	v_mov_b32_e32 v49, v69
	v_mov_b32_e32 v50, v69
	v_mov_b32_e32 v51, v69
	v_mov_b32_e32 v52, 0
	v_mov_b32_e32 v53, v69
	v_mov_b32_e32 v54, v69
	v_mov_b32_e32 v55, v69
	v_mov_b32_e32 v56, 0
	v_mov_b32_e32 v57, v69
	v_mov_b32_e32 v58, v69
	v_mov_b32_e32 v59, v69
	v_mov_b32_e32 v60, 0
	v_mov_b32_e32 v61, v69
	v_mov_b32_e32 v62, v69
	v_mov_b32_e32 v63, v69
	v_readlane_b32 s40, v241, 21
	v_readlane_b32 s41, v241, 22
	v_readlane_b32 s42, v241, 23
	v_readlane_b32 s43, v241, 24
	v_readlane_b32 s37, v241, 18
	v_readlane_b32 s38, v241, 19
	v_readlane_b32 s39, v241, 20

.LBB0_1517:
	s_or_b64 exec, exec, s[0:1]
	s_mov_b32 s0, s74
	s_mov_b32 s3, s76
	s_waitcnt lgkmcnt(0)
	s_barrier
	v_mov_b32_e32 v0, v226
	s_ashr_i32 s2, s0, 3
	s_cmpk_gt_i32 s2, 0x1b7
	v_readfirstlane_b32 s1, v0
	s_cbranch_scc1 .LBB0_1522
	v_bfe_u32 v1, v0, 4, 2
	v_lshrrev_b32_e32 v2, 2, v0
	v_bitop3_b32 v2, v1, v2, 3 bitop3:0x78
	v_lshlrev_b32_e32 v2, 3, v2
	v_lshlrev_b32_e32 v3, 5, v0
	s_mov_b32 s4, 0x7ffff1e0
	v_and_or_b32 v4, v3, s4, v2
	s_movk_i32 s4, 0x9e0
	v_lshlrev_b32_e32 v139, 1, v4
	v_and_or_b32 v2, v3, s4, v2
	s_ashr_i32 s4, s1, 6
	v_bfe_u32 v4, v0, 2, 4
	s_andn2_b32 s1, s1, 63
	s_ashr_i32 s3, s3, 3
	v_or_b32_e32 v142, s1, v4
	s_lshl_b32 s1, s4, 11
	s_and_b32 s16, s0, 7
	s_lshl_b32 s17, s4, 12
	s_sub_i32 s18, 0, s1
	s_lshl_b32 s19, s2, 6
	s_lshl_b32 s20, s3, 6
	v_bitop3_b32 v3, v1, v0, 3 bitop3:0x78
	v_lshlrev_b32_e32 v1, 2, v1
	s_movk_i32 s1, 0xff80
	s_bitcmp1_b32 s0, 3
	v_and_or_b32 v145, v0, s1, v1
	s_cselect_b64 s[0:1], -1, 0
	s_bitcmp1_b32 s3, 0
	v_lshlrev_b32_e32 v2, 1, v2
	v_lshlrev_b32_e32 v128, 4, v3
	v_mov_b32_e32 v129, 0
	v_lshl_or_b32 v143, s4, 5, v4
	s_cselect_b64 s[4:5], -1, 0
	s_add_i32 s31, s17, s18
	v_and_b32_e32 v138, 15, v0
	v_and_b32_e32 v140, 64, v0
	v_or_b32_e32 v141, 0x4000, v2
	s_mul_i32 s16, s16, 10
	v_lshl_add_u64 v[130:131], s[70:71], 0, v[128:129]
	v_lshl_add_u64 v[132:133], s[90:91], 0, v[128:129]
	v_add_u32_e32 v128, 0x6000, v139
	v_or_b32_e32 v144, 0xa000, v2
	s_mov_b64 s[6:7], 0x8000
	s_add_i32 s21, s17, 0x400
	s_add_i32 s22, s17, 0x800
	s_add_i32 s23, s17, 0xc00
	s_add_i32 s24, s31, 0x4000
	s_add_i32 s25, s31, 0x4400
	s_add_i32 s26, s17, 0x6000
	s_mov_b64 s[8:9], 0x8040
	s_add_i32 s27, s17, 0x6400
	s_add_i32 s28, s17, 0x6800
	s_add_i32 s29, s17, 0x6c00
	s_add_i32 s30, s31, 0xa000
	s_add_i32 s31, s31, 0xa400
	s_movk_i32 s33, 0x1600
	s_mov_b64 s[10:11], 0x80
	s_mov_b64 s[12:13], 0x8080
	s_movk_i32 s34, 0x7fff
	s_waitcnt vmcnt(0)
.LBB0_1519:
	s_mul_hi_i32 s14, s2, 0x2e8ba2e9
	s_lshr_b32 s15, s14, 31
	s_ashr_i32 s14, s14, 4
	s_add_i32 s37, s14, s15
	s_lshl_b32 s35, s37, 1
	s_and_b32 s15, s2, 1
	s_add_i32 s38, s35, s16
	s_or_b32 s15, s38, s15
	s_lshl_b32 s35, s15, 8
	s_mul_i32 s14, s37, 0xffffffa8
	v_add_u32_e32 v0, s35, v142
	s_add_i32 s14, s14, s2
	v_ashrrev_i32_e32 v1, 31, v0
	v_lshlrev_b64 v[0:1], 11, v[0:1]
	s_lshl_b32 s14, s14, 6
	s_mov_b32 m0, s17
	v_lshl_add_u64 v[0:1], v[130:131], 0, v[0:1]
	s_and_b32 s36, s14, 0xffffff80
	v_add_u32_e32 v2, s36, v143
	global_load_lds_dwordx4 v[0:1], off
	v_lshl_add_u64 v[4:5], v[0:1], 0, s[6:7]
	s_mov_b32 m0, s21
	s_mov_b64 s[14:15], 0x10000
	v_ashrrev_i32_e32 v3, 31, v2
	global_load_lds_dwordx4 v[4:5], off
	v_lshl_add_u64 v[4:5], v[0:1], 0, s[14:15]
	s_mov_b32 m0, s22
	s_mov_b64 s[14:15], 0x18000
	v_lshlrev_b64 v[2:3], 11, v[2:3]
	global_load_lds_dwordx4 v[4:5], off
	v_lshl_add_u64 v[4:5], v[0:1], 0, s[14:15]
	s_mov_b32 m0, s23
	v_lshl_add_u64 v[2:3], v[132:133], 0, v[2:3]
	global_load_lds_dwordx4 v[4:5], off
	s_mov_b32 m0, s24
	v_lshl_add_u64 v[4:5], v[2:3], 0, s[6:7]
	global_load_lds_dwordx4 v[2:3], off
	s_mov_b32 m0, s25
	s_mov_b64 s[14:15], 0x10040
	global_load_lds_dwordx4 v[4:5], off
	v_lshl_add_u64 v[4:5], v[0:1], 0, 64
	s_mov_b32 m0, s26
	s_mulk_i32 s37, 0x1600
	global_load_lds_dwordx4 v[4:5], off
	v_lshl_add_u64 v[4:5], v[0:1], 0, s[8:9]
	s_mov_b32 m0, s27
	v_cndmask_b32_e64 v6, 0, 1, s[0:1]
	global_load_lds_dwordx4 v[4:5], off
	v_lshl_add_u64 v[4:5], v[0:1], 0, s[14:15]
	s_mov_b32 m0, s28
	s_mov_b64 s[14:15], 0x18040
	global_load_lds_dwordx4 v[4:5], off
	v_lshl_add_u64 v[0:1], v[0:1], 0, s[14:15]
	s_mov_b32 m0, s29
	s_sub_i32 s14, s19, s37
	global_load_lds_dwordx4 v[0:1], off
	v_lshl_add_u64 v[0:1], v[2:3], 0, 64
	s_mov_b32 m0, s30
	s_and_b32 s14, s14, 0xffffff80
	global_load_lds_dwordx4 v[0:1], off
	v_lshl_add_u64 v[0:1], v[2:3], 0, s[8:9]
	s_mov_b32 m0, s31
	s_mov_b32 s37, 2
	global_load_lds_dwordx4 v[0:1], off
	v_add_u32_e32 v0, s14, v143
	v_ashrrev_i32_e32 v1, 31, v0
	v_lshlrev_b64 v[0:1], 11, v[0:1]
	v_lshl_add_u64 v[134:135], v[132:133], 0, v[0:1]
	v_add_u32_e32 v0, s38, v6
	v_lshl_add_u32 v0, v0, 8, v142
	v_ashrrev_i32_e32 v1, 31, v0
	v_lshlrev_b64 v[0:1], 11, v[0:1]
	v_lshl_add_u64 v[136:137], v[130:131], 0, v[0:1]
	s_mov_b64 s[14:15], 0
	s_mov_b32 s38, 0
	v_mov_b32_e32 v0, 0
	v_mov_b32_e32 v1, v129
	v_mov_b32_e32 v2, v129
	v_mov_b32_e32 v3, v129
	v_mov_b32_e32 v4, 0
	v_mov_b32_e32 v5, v129
	v_mov_b32_e32 v6, v129
	v_mov_b32_e32 v7, v129
	v_mov_b32_e32 v8, 0
	v_mov_b32_e32 v9, v129
	v_mov_b32_e32 v10, v129
	v_mov_b32_e32 v11, v129
	v_mov_b32_e32 v12, 0
	v_mov_b32_e32 v13, v129
	v_mov_b32_e32 v14, v129
	v_mov_b32_e32 v15, v129
	v_mov_b32_e32 v16, 0
	v_mov_b32_e32 v17, v129
	v_mov_b32_e32 v18, v129
	v_mov_b32_e32 v19, v129
	v_mov_b32_e32 v20, 0
	v_mov_b32_e32 v21, v129
	v_mov_b32_e32 v22, v129
	v_mov_b32_e32 v23, v129
	v_mov_b32_e32 v24, 0
	v_mov_b32_e32 v25, v129
	v_mov_b32_e32 v26, v129
	v_mov_b32_e32 v27, v129
	v_mov_b32_e32 v28, 0
	v_mov_b32_e32 v29, v129
	v_mov_b32_e32 v30, v129
	v_mov_b32_e32 v31, v129
	v_mov_b32_e32 v32, 0
	v_mov_b32_e32 v33, v129
	v_mov_b32_e32 v34, v129
	v_mov_b32_e32 v35, v129
	v_mov_b32_e32 v36, 0
	v_mov_b32_e32 v37, v129
	v_mov_b32_e32 v38, v129
	v_mov_b32_e32 v39, v129
	v_mov_b32_e32 v44, 0
	v_mov_b32_e32 v45, v129
	v_mov_b32_e32 v46, v129
	v_mov_b32_e32 v47, v129
	v_mov_b32_e32 v52, 0
	v_mov_b32_e32 v53, v129
	v_mov_b32_e32 v54, v129
	v_mov_b32_e32 v55, v129
	v_mov_b32_e32 v60, 0
	v_mov_b32_e32 v61, v129
	v_mov_b32_e32 v62, v129
	v_mov_b32_e32 v63, v129
	v_mov_b32_e32 v68, 0
	v_mov_b32_e32 v69, v129
	v_mov_b32_e32 v70, v129
	v_mov_b32_e32 v71, v129
	v_mov_b32_e32 v76, 0
	v_mov_b32_e32 v77, v129
	v_mov_b32_e32 v78, v129
	v_mov_b32_e32 v79, v129
	v_mov_b32_e32 v84, 0
	v_mov_b32_e32 v85, v129
	v_mov_b32_e32 v86, v129
	v_mov_b32_e32 v87, v129
	v_mov_b32_e32 v40, 0
	v_mov_b32_e32 v41, v129
	v_mov_b32_e32 v42, v129
	v_mov_b32_e32 v43, v129
	v_mov_b32_e32 v48, 0
	v_mov_b32_e32 v49, v129
	v_mov_b32_e32 v50, v129
	v_mov_b32_e32 v51, v129
	v_mov_b32_e32 v56, 0
	v_mov_b32_e32 v57, v129
	v_mov_b32_e32 v58, v129
	v_mov_b32_e32 v59, v129
	v_mov_b32_e32 v64, 0
	v_mov_b32_e32 v65, v129
	v_mov_b32_e32 v66, v129
	v_mov_b32_e32 v67, v129
	v_mov_b32_e32 v72, 0
	v_mov_b32_e32 v73, v129
	v_mov_b32_e32 v74, v129
	v_mov_b32_e32 v75, v129
	v_mov_b32_e32 v80, 0
	v_mov_b32_e32 v81, v129
	v_mov_b32_e32 v82, v129
	v_mov_b32_e32 v83, v129
	v_mov_b32_e32 v88, 0
	v_mov_b32_e32 v89, v129
	v_mov_b32_e32 v90, v129
	v_mov_b32_e32 v91, v129
	v_mov_b32_e32 v92, 0
	v_mov_b32_e32 v93, v129
	v_mov_b32_e32 v94, v129
	v_mov_b32_e32 v95, v129
	v_mov_b32_e32 v96, 0
	v_mov_b32_e32 v97, v129
	v_mov_b32_e32 v98, v129
	v_mov_b32_e32 v99, v129
	v_mov_b32_e32 v100, 0
	v_mov_b32_e32 v101, v129
	v_mov_b32_e32 v102, v129
	v_mov_b32_e32 v103, v129
	v_mov_b32_e32 v104, 0
	v_mov_b32_e32 v105, v129
	v_mov_b32_e32 v106, v129
	v_mov_b32_e32 v107, v129
	v_mov_b32_e32 v108, 0
	v_mov_b32_e32 v109, v129
	v_mov_b32_e32 v110, v129
	v_mov_b32_e32 v111, v129
	v_mov_b32_e32 v112, 0
	v_mov_b32_e32 v113, v129
	v_mov_b32_e32 v114, v129
	v_mov_b32_e32 v115, v129
	v_mov_b32_e32 v116, 0
	v_mov_b32_e32 v117, v129
	v_mov_b32_e32 v118, v129
	v_mov_b32_e32 v119, v129
	v_mov_b32_e32 v120, 0
	v_mov_b32_e32 v121, v129
	v_mov_b32_e32 v122, v129
	v_mov_b32_e32 v123, v129
	v_mov_b32_e32 v124, 0
	v_mov_b32_e32 v125, v129
	v_mov_b32_e32 v126, v129
	v_mov_b32_e32 v127, v129

.LBB0_1574:
	s_or_b64 exec, exec, s[0:1]
	s_mov_b32 s0, s74
	s_mov_b32 s14, s76
	s_waitcnt lgkmcnt(0)
	s_barrier
	v_mov_b32_e32 v0, v226
	s_ashr_i32 s2, s0, 3
	s_cmpk_gt_i32 s2, 0x9f
	v_readfirstlane_b32 s1, v0
	s_cbranch_scc1 .LBB0_1579
	s_ashr_i32 s1, s1, 1
	v_bfe_u32 v1, v0, 2, 4
	s_andn2_b32 s1, s1, 31
	v_or_b32_e32 v83, s1, v1
	v_bfe_u32 v1, v0, 4, 2
	v_bitop3_b32 v3, v1, v0, 3 bitop3:0x78
	v_lshrrev_b32_e32 v2, 2, v0
	v_lshlrev_b32_e32 v68, 4, v3
	v_ashrrev_i32_e32 v3, 1, v0
	v_and_b32_e32 v82, 15, v0
	v_bitop3_b32 v2, v1, v2, 3 bitop3:0x78
	v_and_b32_e32 v84, 0xffffffc0, v3
	s_lshr_b32 s15, s0, 3
	v_lshlrev_b32_e32 v2, 4, v2
	s_and_b32 s18, s0, 7
	v_or_b32_e32 v3, v84, v82
	v_and_b32_e32 v85, 64, v0
	v_lshlrev_b32_e32 v0, 6, v0
	s_movk_i32 s0, 0x13c0
	v_readlane_b32 s4, v241, 17
	v_readlane_b32 s36, v241, 1
	s_ashr_i32 s3, s14, 3
	v_mov_b32_e32 v69, 0
	s_lshl_b32 s19, s1, 6
	v_lshl_or_b32 v86, v3, 6, v2
	v_and_or_b32 v2, v0, s0, v2
	v_lshlrev_b32_e32 v0, 2, v1
	v_readlane_b32 s5, v241, 18
	v_readlane_b32 s6, v241, 19
	v_readlane_b32 s7, v241, 20
	v_readlane_b32 s8, v241, 21
	v_readlane_b32 s9, v241, 22
	v_readlane_b32 s10, v241, 23
	v_readlane_b32 s11, v241, 24
	v_readlane_b32 s46, v241, 11
	v_readlane_b32 s47, v241, 12
	s_mul_i32 s18, s18, 20
	v_lshl_add_u64 v[70:71], s[92:93], 0, v[68:69]
	v_or_b32_e32 v87, 0x2000, v2
	v_add_u32_e32 v88, 0x8000, v86
	v_or_b32_e32 v89, 0xa000, v2
	v_lshl_add_u64 v[72:73], s[4:5], 0, v[68:69]
	s_lshl_b32 s20, s2, 5
	s_lshl_b32 s21, s3, 5
	s_movk_i32 s22, 0x1600
	s_mov_b64 s[0:1], 0x16000
	s_add_i32 s23, s19, 0x400
	s_add_i32 s24, s19, 0x2000
	s_add_i32 s25, s19, 0x2400
	s_add_i32 s26, s19, 0x4000
	s_mov_b64 s[4:5], 0x16040
	s_add_i32 s27, s19, 0x4400
	s_add_i32 s28, s19, 0x6000
	s_add_i32 s29, s19, 0x6400
	s_mov_b64 s[6:7], 0x80
	s_mov_b64 s[8:9], 0x16080
	s_mov_b64 s[10:11], 0xc0
	s_mov_b64 s[12:13], 0x160c0
	s_lshr_b32 s30, s14, 3
	v_mov_b64_e32 v[74:75], s[46:47]
	v_lshlrev_b32_e32 v68, 2, v0
	s_mov_b32 s14, 0x3fb504f3
	v_readlane_b32 s37, v241, 2
	v_readlane_b32 s38, v241, 3
	v_readlane_b32 s39, v241, 4
	v_readlane_b32 s40, v241, 5
	v_readlane_b32 s41, v241, 6
	v_readlane_b32 s42, v241, 7
	v_readlane_b32 s43, v241, 8
	v_readlane_b32 s44, v241, 9
	v_readlane_b32 s45, v241, 10
	v_readlane_b32 s48, v241, 13
	v_readlane_b32 s49, v241, 14
	v_readlane_b32 s50, v241, 15
	v_readlane_b32 s51, v241, 16
	s_waitcnt vmcnt(0)
.LBB0_1576:
	s_ashr_i32 s16, s2, 31
	s_lshr_b32 s16, s16, 27
	s_add_i32 s16, s2, s16
	s_ashr_i32 s16, s16, 5
	s_lshl_b32 s17, s16, 2
	s_and_b32 s31, s2, 3
	s_add_i32 s34, s17, s18
	s_or_b32 s17, s34, s31
	s_lshl_b32 s31, s17, 7
	s_lshl_b32 s35, s16, 10
	s_lshl_b32 s16, s2, 5
	v_add_u32_e32 v2, s31, v83
	s_sub_i32 s16, s16, s35
	s_mov_b32 m0, s19
	s_and_b32 s33, s16, 0xffffff80
	v_mad_i64_i32 v[2:3], s[16:17], v2, s22, v[72:73]
	v_add_u32_e32 v0, s33, v83
	global_load_lds_dwordx4 v[2:3], off
	v_lshl_add_u64 v[4:5], v[2:3], 0, s[0:1]
	s_mov_b32 m0, s23
	v_mad_i64_i32 v[0:1], s[16:17], v0, s22, v[70:71]
	global_load_lds_dwordx4 v[4:5], off
	s_mov_b32 m0, s24
	v_lshl_add_u64 v[4:5], v[0:1], 0, s[0:1]
	global_load_lds_dwordx4 v[0:1], off
	s_mov_b32 m0, s25
	s_sub_i32 s16, s20, s35
	global_load_lds_dwordx4 v[4:5], off
	v_lshl_add_u64 v[4:5], v[2:3], 0, 64
	s_mov_b32 m0, s26
	v_lshl_add_u64 v[2:3], v[2:3], 0, s[4:5]
	global_load_lds_dwordx4 v[4:5], off
	s_mov_b32 m0, s27
	s_and_b32 s36, s15, 3
	global_load_lds_dwordx4 v[2:3], off
	v_lshl_add_u64 v[2:3], v[0:1], 0, 64
	s_mov_b32 m0, s28
	v_lshl_add_u64 v[0:1], v[0:1], 0, s[4:5]
	global_load_lds_dwordx4 v[2:3], off
	s_mov_b32 m0, s29
	s_and_b32 s16, s16, 0xffffff80
	global_load_lds_dwordx4 v[0:1], off
	v_add_u32_e32 v0, s16, v83
	s_add_i32 s34, s34, s36
	v_mad_i64_i32 v[64:65], s[16:17], v0, s22, v[70:71]
	v_lshl_add_u32 v0, s34, 7, v83
	v_mad_i64_i32 v[66:67], s[16:17], v0, s22, v[72:73]
	s_mov_b64 s[16:17], 0
	s_mov_b32 s35, 2
	s_mov_b32 s34, 0
	v_mov_b32_e32 v0, 0
	v_mov_b32_e32 v1, v69
	v_mov_b32_e32 v2, v69
	v_mov_b32_e32 v3, v69
	v_mov_b32_e32 v4, 0
	v_mov_b32_e32 v5, v69
	v_mov_b32_e32 v6, v69
	v_mov_b32_e32 v7, v69
	v_mov_b32_e32 v8, 0
	v_mov_b32_e32 v9, v69
	v_mov_b32_e32 v10, v69
	v_mov_b32_e32 v11, v69
	v_mov_b32_e32 v12, 0
	v_mov_b32_e32 v13, v69
	v_mov_b32_e32 v14, v69
	v_mov_b32_e32 v15, v69
	v_mov_b32_e32 v16, 0
	v_mov_b32_e32 v17, v69
	v_mov_b32_e32 v18, v69
	v_mov_b32_e32 v19, v69
	v_mov_b32_e32 v20, 0
	v_mov_b32_e32 v21, v69
	v_mov_b32_e32 v22, v69
	v_mov_b32_e32 v23, v69
	v_mov_b32_e32 v24, 0
	v_mov_b32_e32 v25, v69
	v_mov_b32_e32 v26, v69
	v_mov_b32_e32 v27, v69
	v_mov_b32_e32 v28, 0
	v_mov_b32_e32 v29, v69
	v_mov_b32_e32 v30, v69
	v_mov_b32_e32 v31, v69
	v_mov_b32_e32 v32, 0
	v_mov_b32_e32 v33, v69
	v_mov_b32_e32 v34, v69
	v_mov_b32_e32 v35, v69
	v_mov_b32_e32 v36, 0
	v_mov_b32_e32 v37, v69
	v_mov_b32_e32 v38, v69
	v_mov_b32_e32 v39, v69
	v_mov_b32_e32 v40, 0
	v_mov_b32_e32 v41, v69
	v_mov_b32_e32 v42, v69
	v_mov_b32_e32 v43, v69
	v_mov_b32_e32 v44, 0
	v_mov_b32_e32 v45, v69
	v_mov_b32_e32 v46, v69
	v_mov_b32_e32 v47, v69
	v_mov_b32_e32 v48, 0
	v_mov_b32_e32 v49, v69
	v_mov_b32_e32 v50, v69
	v_mov_b32_e32 v51, v69
	v_mov_b32_e32 v52, 0
	v_mov_b32_e32 v53, v69
	v_mov_b32_e32 v54, v69
	v_mov_b32_e32 v55, v69
	v_mov_b32_e32 v56, 0
	v_mov_b32_e32 v57, v69
	v_mov_b32_e32 v58, v69
	v_mov_b32_e32 v59, v69
	v_mov_b32_e32 v60, 0
	v_mov_b32_e32 v61, v69
	v_mov_b32_e32 v62, v69
	v_mov_b32_e32 v63, v69

.LBB0_1690:
	s_or_b64 exec, exec, s[0:1]
	s_add_i32 s2, s2, s3
	s_add_i32 s25, s25, s26
	s_xor_b64 s[12:13], s[12:13], s[14:15]
	s_cmpk_gt_i32 s2, 0xdb
	s_cbranch_scc1 .LBB0_1953
	s_waitcnt vmcnt(0)
.LBB0_1691:
	s_mul_hi_i32 s0, s2, 0x2e8ba2e9
	s_lshr_b32 s1, s0, 31
	s_ashr_i32 s0, s0, 3
	s_add_i32 s6, s0, s1
	s_lshl_b32 s4, s6, 1
	s_and_b32 s1, s2, 1
	s_add_i32 s7, s4, s22
	s_or_b32 s1, s7, s1
	s_lshl_b32 s4, s1, 8
	s_mul_i32 s0, s6, 0xffffffd4
	v_add_u32_e32 v0, s4, v147
	s_add_i32 s0, s0, s2
	v_ashrrev_i32_e32 v1, 31, v0
	v_lshlrev_b64 v[0:1], 11, v[0:1]
	s_lshl_b32 s44, s0, 6
	s_mov_b32 m0, s23
	v_lshl_add_u64 v[0:1], v[132:133], 0, v[0:1]
	s_and_b32 s5, s44, 0xffffff80
	v_add_u32_e32 v2, s5, v148
	global_load_lds_dwordx4 v[0:1], off
	v_lshl_add_u64 v[4:5], v[0:1], 0, s[16:17]
	s_mov_b32 m0, s27
	s_mov_b64 s[0:1], 0x10000
	v_ashrrev_i32_e32 v3, 31, v2
	global_load_lds_dwordx4 v[4:5], off
	v_lshl_add_u64 v[4:5], v[0:1], 0, s[0:1]
	s_mov_b32 m0, s28
	s_mov_b64 s[0:1], 0x18000
	v_lshlrev_b64 v[2:3], 11, v[2:3]
	global_load_lds_dwordx4 v[4:5], off
	v_lshl_add_u64 v[4:5], v[0:1], 0, s[0:1]
	s_mov_b32 m0, s29
	v_lshl_add_u64 v[2:3], v[136:137], 0, v[2:3]
	global_load_lds_dwordx4 v[4:5], off
	s_mov_b32 m0, s30
	v_lshl_add_u64 v[4:5], v[2:3], 0, s[16:17]
	global_load_lds_dwordx4 v[2:3], off
	s_mov_b32 m0, s31
	s_mov_b64 s[0:1], 0x10040
	global_load_lds_dwordx4 v[4:5], off
	v_lshl_add_u64 v[4:5], v[0:1], 0, 64
	s_mov_b32 m0, s33
	s_mulk_i32 s6, 0xb00
	global_load_lds_dwordx4 v[4:5], off
	v_lshl_add_u64 v[4:5], v[0:1], 0, s[18:19]
	s_mov_b32 m0, s34
	v_cndmask_b32_e64 v6, 0, 1, s[12:13]
	global_load_lds_dwordx4 v[4:5], off
	v_lshl_add_u64 v[4:5], v[0:1], 0, s[0:1]
	s_mov_b32 m0, s35
	s_mov_b64 s[0:1], 0x18040
	global_load_lds_dwordx4 v[4:5], off
	v_lshl_add_u64 v[0:1], v[0:1], 0, s[0:1]
	s_mov_b32 m0, s36
	s_sub_i32 s0, s25, s6
	global_load_lds_dwordx4 v[0:1], off
	v_lshl_add_u64 v[0:1], v[2:3], 0, 64
	s_mov_b32 m0, s37
	s_and_b32 s0, s0, 0xffffff80
	global_load_lds_dwordx4 v[0:1], off
	v_lshl_add_u64 v[0:1], v[2:3], 0, s[18:19]
	s_mov_b32 m0, s38
	s_mov_b32 s6, 2
	global_load_lds_dwordx4 v[0:1], off
	v_add_u32_e32 v0, s0, v148
	v_ashrrev_i32_e32 v1, 31, v0
	v_lshlrev_b64 v[0:1], 11, v[0:1]
	v_lshl_add_u64 v[140:141], v[134:135], 0, v[0:1]
	v_add_u32_e32 v0, s7, v6
	v_lshl_add_u32 v0, v0, 8, v147
	v_ashrrev_i32_e32 v1, 31, v0
	v_lshlrev_b64 v[0:1], 11, v[0:1]
	v_lshl_add_u64 v[142:143], v[132:133], 0, v[0:1]
	s_mov_b64 s[0:1], 0
	s_mov_b32 s7, 0
	v_mov_b32_e32 v0, 0
	v_mov_b32_e32 v1, v131
	v_mov_b32_e32 v2, v131
	v_mov_b32_e32 v3, v131
	v_mov_b32_e32 v4, 0
	v_mov_b32_e32 v5, v131
	v_mov_b32_e32 v6, v131
	v_mov_b32_e32 v7, v131
	v_mov_b32_e32 v8, 0
	v_mov_b32_e32 v9, v131
	v_mov_b32_e32 v10, v131
	v_mov_b32_e32 v11, v131
	v_mov_b32_e32 v12, 0
	v_mov_b32_e32 v13, v131
	v_mov_b32_e32 v14, v131
	v_mov_b32_e32 v15, v131
	v_mov_b32_e32 v16, 0
	v_mov_b32_e32 v17, v131
	v_mov_b32_e32 v18, v131
	v_mov_b32_e32 v19, v131
	v_mov_b32_e32 v20, 0
	v_mov_b32_e32 v21, v131
	v_mov_b32_e32 v22, v131
	v_mov_b32_e32 v23, v131
	v_mov_b32_e32 v24, 0
	v_mov_b32_e32 v25, v131
	v_mov_b32_e32 v26, v131
	v_mov_b32_e32 v27, v131
	v_mov_b32_e32 v28, 0
	v_mov_b32_e32 v29, v131
	v_mov_b32_e32 v30, v131
	v_mov_b32_e32 v31, v131
	v_mov_b32_e32 v32, 0
	v_mov_b32_e32 v33, v131
	v_mov_b32_e32 v34, v131
	v_mov_b32_e32 v35, v131
	v_mov_b32_e32 v36, 0
	v_mov_b32_e32 v37, v131
	v_mov_b32_e32 v38, v131
	v_mov_b32_e32 v39, v131
	v_mov_b32_e32 v44, 0
	v_mov_b32_e32 v45, v131
	v_mov_b32_e32 v46, v131
	v_mov_b32_e32 v47, v131
	v_mov_b32_e32 v52, 0
	v_mov_b32_e32 v53, v131
	v_mov_b32_e32 v54, v131
	v_mov_b32_e32 v55, v131
	v_mov_b32_e32 v60, 0
	v_mov_b32_e32 v61, v131
	v_mov_b32_e32 v62, v131
	v_mov_b32_e32 v63, v131
	v_mov_b32_e32 v68, 0
	v_mov_b32_e32 v69, v131
	v_mov_b32_e32 v70, v131
	v_mov_b32_e32 v71, v131
	v_mov_b32_e32 v76, 0
	v_mov_b32_e32 v77, v131
	v_mov_b32_e32 v78, v131
	v_mov_b32_e32 v79, v131
	v_mov_b32_e32 v84, 0
	v_mov_b32_e32 v85, v131
	v_mov_b32_e32 v86, v131
	v_mov_b32_e32 v87, v131
	v_mov_b32_e32 v40, 0
	v_mov_b32_e32 v41, v131
	v_mov_b32_e32 v42, v131
	v_mov_b32_e32 v43, v131
	v_mov_b32_e32 v48, 0
	v_mov_b32_e32 v49, v131
	v_mov_b32_e32 v50, v131
	v_mov_b32_e32 v51, v131
	v_mov_b32_e32 v56, 0
	v_mov_b32_e32 v57, v131
	v_mov_b32_e32 v58, v131
	v_mov_b32_e32 v59, v131
	v_mov_b32_e32 v64, 0
	v_mov_b32_e32 v65, v131
	v_mov_b32_e32 v66, v131
	v_mov_b32_e32 v67, v131
	v_mov_b32_e32 v72, 0
	v_mov_b32_e32 v73, v131
	v_mov_b32_e32 v74, v131
	v_mov_b32_e32 v75, v131
	v_mov_b32_e32 v80, 0
	v_mov_b32_e32 v81, v131
	v_mov_b32_e32 v82, v131
	v_mov_b32_e32 v83, v131
	v_mov_b32_e32 v88, 0
	v_mov_b32_e32 v89, v131
	v_mov_b32_e32 v90, v131
	v_mov_b32_e32 v91, v131
	v_mov_b32_e32 v92, 0
	v_mov_b32_e32 v93, v131
	v_mov_b32_e32 v94, v131
	v_mov_b32_e32 v95, v131
	v_mov_b32_e32 v96, 0
	v_mov_b32_e32 v97, v131
	v_mov_b32_e32 v98, v131
	v_mov_b32_e32 v99, v131
	v_mov_b32_e32 v100, 0
	v_mov_b32_e32 v101, v131
	v_mov_b32_e32 v102, v131
	v_mov_b32_e32 v103, v131
	v_mov_b32_e32 v104, 0
	v_mov_b32_e32 v105, v131
	v_mov_b32_e32 v106, v131
	v_mov_b32_e32 v107, v131
	v_mov_b32_e32 v108, 0
	v_mov_b32_e32 v109, v131
	v_mov_b32_e32 v110, v131
	v_mov_b32_e32 v111, v131
	v_mov_b32_e32 v112, 0
	v_mov_b32_e32 v113, v131
	v_mov_b32_e32 v114, v131
	v_mov_b32_e32 v115, v131
	v_mov_b32_e32 v116, 0
	v_mov_b32_e32 v117, v131
	v_mov_b32_e32 v118, v131
	v_mov_b32_e32 v119, v131
	v_mov_b32_e32 v120, 0
	v_mov_b32_e32 v121, v131
	v_mov_b32_e32 v122, v131
	v_mov_b32_e32 v123, v131
	v_mov_b32_e32 v124, 0
	v_mov_b32_e32 v125, v131
	v_mov_b32_e32 v126, v131
	v_mov_b32_e32 v127, v131

.LBB0_2119:
	s_mul_hi_i32 s30, s2, 0x66666667
	s_lshr_b32 s31, s30, 31
	s_ashr_i32 s30, s30, 4
	s_add_i32 s30, s30, s31
	s_lshl_b32 s34, s30, 2
	s_and_b32 s31, s2, 3
	s_add_i32 s34, s34, s33
	s_or_b32 s31, s34, s31
	s_lshl_b32 s54, s31, 7
	s_mulk_i32 s30, 0xfb00
	v_add_u32_e32 v0, s54, v80
	s_add_i32 s53, s37, s30
	v_ashrrev_i32_e32 v1, 31, v0
	s_and_b32 s30, s53, 0xffffff80
	v_add_u32_e32 v2, s30, v80
	v_lshlrev_b64 v[0:1], 9, v[0:1]
	s_mov_b32 m0, s36
	v_ashrrev_i32_e32 v3, 31, v2
	v_lshl_add_u64 v[78:79], v[74:75], 0, v[0:1]
	v_lshlrev_b64 v[2:3], 9, v[2:3]
	global_load_lds_dwordx4 v[78:79], off
	v_lshl_add_u64 v[0:1], v[78:79], 0, s[0:1]
	s_mov_b32 m0, s39
	v_lshl_add_u64 v[68:69], v[72:73], 0, v[2:3]
	global_load_lds_dwordx4 v[0:1], off
	s_mov_b32 m0, s40
	v_lshl_add_u64 v[0:1], v[68:69], 0, s[0:1]
	global_load_lds_dwordx4 v[68:69], off
	s_mov_b32 m0, s41
	v_lshl_add_u64 v[4:5], v[78:79], 0, s[8:9]
	global_load_lds_dwordx4 v[0:1], off
	v_lshl_add_u64 v[0:1], v[78:79], 0, 64
	s_mov_b32 m0, s42
	v_lshl_add_u64 v[6:7], v[78:79], 0, s[6:7]
	global_load_lds_dwordx4 v[0:1], off
	v_lshl_add_u64 v[0:1], v[78:79], 0, s[4:5]
	s_mov_b32 m0, s43
	v_lshl_add_u64 v[2:3], v[68:69], 0, s[8:9]
	global_load_lds_dwordx4 v[0:1], off
	v_lshl_add_u64 v[0:1], v[68:69], 0, 64
	s_mov_b32 m0, s44
	v_lshl_add_u64 v[90:91], v[78:79], 0, s[12:13]
	global_load_lds_dwordx4 v[0:1], off
	v_lshl_add_u64 v[0:1], v[68:69], 0, s[4:5]
	s_mov_b32 m0, s45
	v_lshl_add_u64 v[92:93], v[78:79], 0, s[10:11]
	global_load_lds_dwordx4 v[0:1], off
	s_waitcnt vmcnt(4)
	s_waitcnt lgkmcnt(0)
	s_barrier
	s_mov_b32 m0, s46
	v_lshl_add_u64 v[0:1], v[68:69], 0, s[6:7]
	global_load_lds_dwordx4 v[4:5], off
	s_mov_b32 m0, s47
	s_nop 0
	global_load_lds_dwordx4 v[6:7], off
	s_mov_b32 m0, s48
	s_nop 0
	global_load_lds_dwordx4 v[2:3], off
	s_mov_b32 m0, s49
	s_nop 0
	global_load_lds_dwordx4 v[0:1], off
	ds_read_b128 v[0:3], v82
	ds_read_b128 v[4:7], v82 offset:1024
	ds_read_b128 v[8:11], v82 offset:2048
	ds_read_b128 v[12:15], v82 offset:3072
	ds_read_b128 v[16:19], v83
	ds_read_b128 v[20:23], v83 offset:1024
	ds_read_b128 v[24:27], v83 offset:2048
	ds_read_b128 v[28:31], v83 offset:3072
	s_waitcnt lgkmcnt(0)
	s_waitcnt vmcnt(4)
	s_waitcnt lgkmcnt(0)
	s_barrier
	s_mov_b32 m0, s36
	v_mfma_f32_16x16x32_bf16 v[32:35], v[16:19], v[0:3], 0
	global_load_lds_dwordx4 v[90:91], off
	s_mov_b32 m0, s39
	v_mfma_f32_16x16x32_bf16 v[36:39], v[20:23], v[0:3], 0
	global_load_lds_dwordx4 v[92:93], off
	s_mov_b32 m0, s40
	v_mfma_f32_16x16x32_bf16 v[40:43], v[24:27], v[0:3], 0
	v_mfma_f32_16x16x32_bf16 v[0:3], v[28:31], v[0:3], 0
	v_mfma_f32_16x16x32_bf16 v[44:47], v[16:19], v[4:7], 0
	v_mfma_f32_16x16x32_bf16 v[48:51], v[20:23], v[4:7], 0
	v_mfma_f32_16x16x32_bf16 v[52:55], v[24:27], v[4:7], 0
	v_mfma_f32_16x16x32_bf16 v[4:7], v[28:31], v[4:7], 0
	v_mfma_f32_16x16x32_bf16 v[56:59], v[16:19], v[8:11], 0
	v_mfma_f32_16x16x32_bf16 v[60:63], v[20:23], v[8:11], 0
	v_mfma_f32_16x16x32_bf16 v[64:67], v[24:27], v[8:11], 0
	v_mfma_f32_16x16x32_bf16 v[8:11], v[28:31], v[8:11], 0
	v_mfma_f32_16x16x32_bf16 v[16:19], v[16:19], v[12:15], 0
	v_mfma_f32_16x16x32_bf16 v[20:23], v[20:23], v[12:15], 0
	v_mfma_f32_16x16x32_bf16 v[24:27], v[24:27], v[12:15], 0
	v_mfma_f32_16x16x32_bf16 v[12:15], v[28:31], v[12:15], 0
	v_lshl_add_u64 v[30:31], v[68:69], 0, s[12:13]
	v_lshl_add_u64 v[28:29], v[68:69], 0, s[10:11]
	global_load_lds_dwordx4 v[30:31], off
	s_mov_b32 m0, s41
	s_nop 0
	global_load_lds_dwordx4 v[28:29], off
	ds_read_b128 v[28:31], v85
	ds_read_b128 v[90:93], v85 offset:1024
	ds_read_b128 v[94:97], v85 offset:2048
	ds_read_b128 v[98:101], v85 offset:3072
	ds_read_b128 v[102:105], v86
	ds_read_b128 v[106:109], v86 offset:1024
	ds_read_b128 v[110:113], v86 offset:2048
	ds_read_b128 v[114:117], v86 offset:3072
	s_waitcnt lgkmcnt(0)
	s_waitcnt vmcnt(4)
	s_waitcnt lgkmcnt(0)
	s_barrier
	v_mfma_f32_16x16x32_bf16 v[32:35], v[102:105], v[28:31], v[32:35]
	s_mov_b32 m0, s42
	v_mfma_f32_16x16x32_bf16 v[36:39], v[106:109], v[28:31], v[36:39]
	v_mfma_f32_16x16x32_bf16 v[40:43], v[110:113], v[28:31], v[40:43]
	v_mfma_f32_16x16x32_bf16 v[0:3], v[114:117], v[28:31], v[0:3]
	v_mfma_f32_16x16x32_bf16 v[28:31], v[102:105], v[90:93], v[44:47]
	v_mfma_f32_16x16x32_bf16 v[44:47], v[106:109], v[90:93], v[48:51]
	v_mfma_f32_16x16x32_bf16 v[48:51], v[110:113], v[90:93], v[52:55]
	v_mfma_f32_16x16x32_bf16 v[4:7], v[114:117], v[90:93], v[4:7]
	v_lshl_add_u64 v[90:91], v[78:79], 0, s[16:17]
	v_lshl_add_u64 v[92:93], v[78:79], 0, s[14:15]
	global_load_lds_dwordx4 v[90:91], off
	s_mov_b32 m0, s43
	v_mfma_f32_16x16x32_bf16 v[52:55], v[102:105], v[94:97], v[56:59]
	global_load_lds_dwordx4 v[92:93], off
	s_mov_b32 m0, s44
	v_mfma_f32_16x16x32_bf16 v[56:59], v[106:109], v[94:97], v[60:63]
	v_mfma_f32_16x16x32_bf16 v[60:63], v[110:113], v[94:97], v[64:67]
	s_nop 2
	v_lshl_add_u64 v[66:67], v[68:69], 0, s[16:17]
	v_lshl_add_u64 v[64:65], v[68:69], 0, s[14:15]
	global_load_lds_dwordx4 v[66:67], off
	s_mov_b32 m0, s45
	v_mfma_f32_16x16x32_bf16 v[8:11], v[114:117], v[94:97], v[8:11]
	global_load_lds_dwordx4 v[64:65], off
	s_mov_b32 m0, s46
	v_mfma_f32_16x16x32_bf16 v[16:19], v[102:105], v[98:101], v[16:19]
	v_mfma_f32_16x16x32_bf16 v[20:23], v[106:109], v[98:101], v[20:23]
	v_mfma_f32_16x16x32_bf16 v[24:27], v[110:113], v[98:101], v[24:27]
	v_mfma_f32_16x16x32_bf16 v[12:15], v[114:117], v[98:101], v[12:15]
	ds_read_b128 v[64:67], v87
	ds_read_b128 v[90:93], v87 offset:1024
	ds_read_b128 v[94:97], v87 offset:2048
	ds_read_b128 v[98:101], v87 offset:3072
	ds_read_b128 v[102:105], v88
	ds_read_b128 v[106:109], v88 offset:1024
	ds_read_b128 v[110:113], v88 offset:2048
	ds_read_b128 v[114:117], v88 offset:3072
	s_waitcnt lgkmcnt(0)
	s_waitcnt vmcnt(4)
	s_waitcnt lgkmcnt(0)
	s_barrier
	v_mfma_f32_16x16x32_bf16 v[28:31], v[102:105], v[90:93], v[28:31]
	v_mfma_f32_16x16x32_bf16 v[44:47], v[106:109], v[90:93], v[44:47]
	v_mfma_f32_16x16x32_bf16 v[48:51], v[110:113], v[90:93], v[48:51]
	v_mfma_f32_16x16x32_bf16 v[4:7], v[114:117], v[90:93], v[4:7]
	v_lshl_add_u64 v[90:91], v[78:79], 0, s[20:21]
	v_lshl_add_u64 v[92:93], v[78:79], 0, s[18:19]
	global_load_lds_dwordx4 v[90:91], off
	s_mov_b32 m0, s47
	v_mfma_f32_16x16x32_bf16 v[32:35], v[102:105], v[64:67], v[32:35]
	global_load_lds_dwordx4 v[92:93], off
	s_mov_b32 m0, s48
	v_mfma_f32_16x16x32_bf16 v[36:39], v[106:109], v[64:67], v[36:39]
	v_mfma_f32_16x16x32_bf16 v[40:43], v[110:113], v[64:67], v[40:43]
	v_mfma_f32_16x16x32_bf16 v[0:3], v[114:117], v[64:67], v[0:3]
	v_lshl_add_u64 v[66:67], v[68:69], 0, s[20:21]
	v_lshl_add_u64 v[64:65], v[68:69], 0, s[18:19]
	global_load_lds_dwordx4 v[66:67], off
	s_mov_b32 m0, s49
	v_mfma_f32_16x16x32_bf16 v[52:55], v[102:105], v[94:97], v[52:55]
	global_load_lds_dwordx4 v[64:65], off
	s_mov_b32 m0, s36
	v_mfma_f32_16x16x32_bf16 v[56:59], v[106:109], v[94:97], v[56:59]
	v_mfma_f32_16x16x32_bf16 v[60:63], v[110:113], v[94:97], v[60:63]
	v_mfma_f32_16x16x32_bf16 v[8:11], v[114:117], v[94:97], v[8:11]
	v_mfma_f32_16x16x32_bf16 v[16:19], v[102:105], v[98:101], v[16:19]
	v_mfma_f32_16x16x32_bf16 v[20:23], v[106:109], v[98:101], v[20:23]
	v_mfma_f32_16x16x32_bf16 v[24:27], v[110:113], v[98:101], v[24:27]
	v_mfma_f32_16x16x32_bf16 v[12:15], v[114:117], v[98:101], v[12:15]
	ds_read_b128 v[64:67], v82
	ds_read_b128 v[90:93], v82 offset:1024
	ds_read_b128 v[94:97], v82 offset:2048
	ds_read_b128 v[98:101], v82 offset:3072
	ds_read_b128 v[102:105], v83
	ds_read_b128 v[106:109], v83 offset:1024
	ds_read_b128 v[110:113], v83 offset:2048
	ds_read_b128 v[114:117], v83 offset:3072
	s_waitcnt lgkmcnt(0)
	s_waitcnt vmcnt(4)
	s_waitcnt lgkmcnt(0)
	s_barrier
	v_mfma_f32_16x16x32_bf16 v[28:31], v[102:105], v[90:93], v[28:31]
	v_mfma_f32_16x16x32_bf16 v[44:47], v[106:109], v[90:93], v[44:47]
	v_mfma_f32_16x16x32_bf16 v[48:51], v[110:113], v[90:93], v[48:51]
	v_mfma_f32_16x16x32_bf16 v[4:7], v[114:117], v[90:93], v[4:7]
	v_lshl_add_u64 v[90:91], v[78:79], 0, s[24:25]
	v_lshl_add_u64 v[92:93], v[78:79], 0, s[22:23]
	global_load_lds_dwordx4 v[90:91], off
	s_mov_b32 m0, s39
	v_mfma_f32_16x16x32_bf16 v[32:35], v[102:105], v[64:67], v[32:35]
	global_load_lds_dwordx4 v[92:93], off
	s_mov_b32 m0, s40
	v_mfma_f32_16x16x32_bf16 v[36:39], v[106:109], v[64:67], v[36:39]
	v_mfma_f32_16x16x32_bf16 v[40:43], v[110:113], v[64:67], v[40:43]
	v_mfma_f32_16x16x32_bf16 v[0:3], v[114:117], v[64:67], v[0:3]
	v_lshl_add_u64 v[66:67], v[68:69], 0, s[24:25]
	v_lshl_add_u64 v[64:65], v[68:69], 0, s[22:23]
	global_load_lds_dwordx4 v[66:67], off
	s_mov_b32 m0, s41
	v_mfma_f32_16x16x32_bf16 v[52:55], v[102:105], v[94:97], v[52:55]
	global_load_lds_dwordx4 v[64:65], off
	s_mov_b32 m0, s42
	v_mfma_f32_16x16x32_bf16 v[56:59], v[106:109], v[94:97], v[56:59]
	v_mfma_f32_16x16x32_bf16 v[60:63], v[110:113], v[94:97], v[60:63]
	v_mfma_f32_16x16x32_bf16 v[8:11], v[114:117], v[94:97], v[8:11]
	v_mfma_f32_16x16x32_bf16 v[16:19], v[102:105], v[98:101], v[16:19]
	v_mfma_f32_16x16x32_bf16 v[20:23], v[106:109], v[98:101], v[20:23]
	v_mfma_f32_16x16x32_bf16 v[24:27], v[110:113], v[98:101], v[24:27]
	v_mfma_f32_16x16x32_bf16 v[12:15], v[114:117], v[98:101], v[12:15]
	ds_read_b128 v[64:67], v85
	ds_read_b128 v[90:93], v85 offset:1024
	ds_read_b128 v[94:97], v85 offset:2048
	ds_read_b128 v[98:101], v85 offset:3072
	ds_read_b128 v[102:105], v86
	ds_read_b128 v[106:109], v86 offset:1024
	ds_read_b128 v[110:113], v86 offset:2048
	ds_read_b128 v[114:117], v86 offset:3072
	s_waitcnt lgkmcnt(0)
	s_waitcnt vmcnt(4)
	s_waitcnt lgkmcnt(0)
	s_barrier
	v_mfma_f32_16x16x32_bf16 v[32:35], v[102:105], v[64:67], v[32:35]
	v_mfma_f32_16x16x32_bf16 v[36:39], v[106:109], v[64:67], v[36:39]
	v_mfma_f32_16x16x32_bf16 v[40:43], v[110:113], v[64:67], v[40:43]
	v_mfma_f32_16x16x32_bf16 v[0:3], v[114:117], v[64:67], v[0:3]
	v_lshl_add_u64 v[64:65], v[68:69], 0, s[26:27]
	v_lshl_add_u64 v[66:67], v[68:69], 0, s[28:29]
	v_lshl_add_u64 v[68:69], v[78:79], 0, s[28:29]
	v_lshl_add_u64 v[78:79], v[78:79], 0, s[26:27]
	global_load_lds_dwordx4 v[68:69], off
	s_mov_b32 m0, s43
	v_mfma_f32_16x16x32_bf16 v[28:31], v[102:105], v[90:93], v[28:31]
	global_load_lds_dwordx4 v[78:79], off
	s_mov_b32 m0, s44
	v_mfma_f32_16x16x32_bf16 v[44:47], v[106:109], v[90:93], v[44:47]
	global_load_lds_dwordx4 v[66:67], off
	s_mov_b32 m0, s45
	v_mfma_f32_16x16x32_bf16 v[48:51], v[110:113], v[90:93], v[48:51]
	global_load_lds_dwordx4 v[64:65], off
	v_or_b32_e32 v78, s30, v84
	v_mfma_f32_16x16x32_bf16 v[4:7], v[114:117], v[90:93], v[4:7]
	v_cmp_lt_i32_e32 vcc, s50, v78
	v_mfma_f32_16x16x32_bf16 v[52:55], v[102:105], v[94:97], v[52:55]
	v_mfma_f32_16x16x32_bf16 v[56:59], v[106:109], v[94:97], v[56:59]
	v_mfma_f32_16x16x32_bf16 v[60:63], v[110:113], v[94:97], v[60:63]
	v_mfma_f32_16x16x32_bf16 v[8:11], v[114:117], v[94:97], v[8:11]
	v_mfma_f32_16x16x32_bf16 v[16:19], v[102:105], v[98:101], v[16:19]
	v_mfma_f32_16x16x32_bf16 v[20:23], v[106:109], v[98:101], v[20:23]
	v_mfma_f32_16x16x32_bf16 v[24:27], v[110:113], v[98:101], v[24:27]
	v_mfma_f32_16x16x32_bf16 v[12:15], v[114:117], v[98:101], v[12:15]
	ds_read_b128 v[64:67], v87
	ds_read_b128 v[90:93], v87 offset:1024
	ds_read_b128 v[94:97], v87 offset:2048
	ds_read_b128 v[98:101], v87 offset:3072
	ds_read_b128 v[102:105], v88
	ds_read_b128 v[106:109], v88 offset:1024
	ds_read_b128 v[110:113], v88 offset:2048
	ds_read_b128 v[114:117], v88 offset:3072
	s_waitcnt lgkmcnt(0)
	s_waitcnt vmcnt(4)
	s_waitcnt lgkmcnt(0)
	s_barrier
	v_mfma_f32_16x16x32_bf16 v[32:35], v[102:105], v[64:67], v[32:35]
	v_mfma_f32_16x16x32_bf16 v[36:39], v[106:109], v[64:67], v[36:39]
	v_mfma_f32_16x16x32_bf16 v[40:43], v[110:113], v[64:67], v[40:43]
	v_mfma_f32_16x16x32_bf16 v[0:3], v[114:117], v[64:67], v[0:3]
	v_mfma_f32_16x16x32_bf16 v[28:31], v[102:105], v[90:93], v[28:31]
	v_mfma_f32_16x16x32_bf16 v[44:47], v[106:109], v[90:93], v[44:47]
	v_mfma_f32_16x16x32_bf16 v[48:51], v[110:113], v[90:93], v[48:51]
	v_mfma_f32_16x16x32_bf16 v[4:7], v[114:117], v[90:93], v[4:7]
	v_mfma_f32_16x16x32_bf16 v[52:55], v[102:105], v[94:97], v[52:55]
	v_mfma_f32_16x16x32_bf16 v[56:59], v[106:109], v[94:97], v[56:59]
	v_mfma_f32_16x16x32_bf16 v[60:63], v[110:113], v[94:97], v[60:63]
	v_mfma_f32_16x16x32_bf16 v[8:11], v[114:117], v[94:97], v[8:11]
	v_mfma_f32_16x16x32_bf16 v[16:19], v[102:105], v[98:101], v[16:19]
	v_mfma_f32_16x16x32_bf16 v[20:23], v[106:109], v[98:101], v[20:23]
	v_mfma_f32_16x16x32_bf16 v[24:27], v[110:113], v[98:101], v[24:27]
	v_mfma_f32_16x16x32_bf16 v[12:15], v[114:117], v[98:101], v[12:15]
	ds_read_b128 v[64:67], v82
	ds_read_b128 v[90:93], v82 offset:1024
	ds_read_b128 v[94:97], v82 offset:2048
	ds_read_b128 v[98:101], v82 offset:3072
	ds_read_b128 v[102:105], v83
	ds_read_b128 v[106:109], v83 offset:1024
	ds_read_b128 v[110:113], v83 offset:2048
	ds_read_b128 v[114:117], v83 offset:3072
	s_waitcnt lgkmcnt(0)
	s_waitcnt vmcnt(0)
	s_waitcnt lgkmcnt(0)
	s_barrier
	v_mfma_f32_16x16x32_bf16 v[32:35], v[102:105], v[64:67], v[32:35]
	v_mfma_f32_16x16x32_bf16 v[36:39], v[106:109], v[64:67], v[36:39]
	v_mfma_f32_16x16x32_bf16 v[40:43], v[110:113], v[64:67], v[40:43]
	v_mfma_f32_16x16x32_bf16 v[0:3], v[114:117], v[64:67], v[0:3]
	v_mfma_f32_16x16x32_bf16 v[118:121], v[102:105], v[90:93], v[28:31]
	v_mfma_f32_16x16x32_bf16 v[122:125], v[106:109], v[90:93], v[44:47]
	v_mfma_f32_16x16x32_bf16 v[48:51], v[110:113], v[90:93], v[48:51]
	v_mfma_f32_16x16x32_bf16 v[4:7], v[114:117], v[90:93], v[4:7]
	v_mfma_f32_16x16x32_bf16 v[52:55], v[102:105], v[94:97], v[52:55]
	v_mfma_f32_16x16x32_bf16 v[90:93], v[106:109], v[94:97], v[56:59]
	v_mfma_f32_16x16x32_bf16 v[126:129], v[110:113], v[94:97], v[60:63]
	v_mfma_f32_16x16x32_bf16 v[94:97], v[114:117], v[94:97], v[8:11]
	v_mfma_f32_16x16x32_bf16 v[16:19], v[102:105], v[98:101], v[16:19]
	v_mfma_f32_16x16x32_bf16 v[102:105], v[106:109], v[98:101], v[20:23]
	v_mfma_f32_16x16x32_bf16 v[106:109], v[110:113], v[98:101], v[24:27]
	v_mfma_f32_16x16x32_bf16 v[98:101], v[114:117], v[98:101], v[12:15]
	ds_read_b128 v[8:11], v85
	ds_read_b128 v[20:23], v85 offset:1024
	ds_read_b128 v[110:113], v85 offset:2048
	ds_read_b128 v[114:117], v85 offset:3072
	ds_read_b128 v[130:133], v86
	ds_read_b128 v[134:137], v86 offset:1024
	ds_read_b128 v[138:141], v86 offset:2048
	ds_read_b128 v[142:145], v86 offset:3072
	s_waitcnt lgkmcnt(0)
	s_waitcnt lgkmcnt(0)
	s_barrier
	v_mfma_f32_16x16x32_bf16 v[66:69], v[130:133], v[8:11], v[32:35]
	v_mfma_f32_16x16x32_bf16 v[44:47], v[134:137], v[8:11], v[36:39]
	v_mfma_f32_16x16x32_bf16 v[28:31], v[138:141], v[8:11], v[40:43]
	v_mfma_f32_16x16x32_bf16 v[12:15], v[142:145], v[8:11], v[0:3]
	v_mfma_f32_16x16x32_bf16 v[62:65], v[130:133], v[20:23], v[118:121]
	v_mfma_f32_16x16x32_bf16 v[40:43], v[134:137], v[20:23], v[122:125]
	v_mfma_f32_16x16x32_bf16 v[24:27], v[138:141], v[20:23], v[48:51]
	v_mfma_f32_16x16x32_bf16 v[8:11], v[142:145], v[20:23], v[4:7]
	v_mfma_f32_16x16x32_bf16 v[58:61], v[130:133], v[110:113], v[52:55]
	v_mfma_f32_16x16x32_bf16 v[36:39], v[134:137], v[110:113], v[90:93]
	v_mfma_f32_16x16x32_bf16 v[20:23], v[138:141], v[110:113], v[126:129]
	v_mfma_f32_16x16x32_bf16 v[4:7], v[142:145], v[110:113], v[94:97]
	v_mfma_f32_16x16x32_bf16 v[48:51], v[130:133], v[114:117], v[16:19]
	v_mfma_f32_16x16x32_bf16 v[32:35], v[134:137], v[114:117], v[102:105]
	v_mfma_f32_16x16x32_bf16 v[16:19], v[138:141], v[114:117], v[106:109]
	v_mfma_f32_16x16x32_bf16 v[0:3], v[142:145], v[114:117], v[98:101]
	s_and_saveexec_b64 s[34:35], vcc
	s_xor_b64 s[34:35], exec, s[34:35]
	s_cbranch_execz .LBB0_2122
	s_cmpk_gt_u32 s53, 0x3ff
	s_cbranch_scc1 .LBB0_2135
	v_readlane_b32 s56, v241, 57
	v_mov_b32_e32 v79, v71
	v_readlane_b32 s68, v240, 5
	v_readlane_b32 s69, v240, 6
	v_readlane_b32 s57, v241, 58
	v_readlane_b32 s58, v241, 59
	v_lshl_add_u64 v[52:53], v[78:79], 2, s[68:69]
	global_load_dwordx4 v[54:57], v[52:53], off
	v_readlane_b32 s59, v241, 60
	v_readlane_b32 s60, v241, 61
	v_readlane_b32 s61, v241, 62
	v_readlane_b32 s62, v241, 63
	v_readlane_b32 s63, v240, 0
	v_readlane_b32 s64, v240, 1
	v_readlane_b32 s65, v240, 2
	v_readlane_b32 s66, v240, 3
	v_readlane_b32 s67, v240, 4
	v_readlane_b32 s70, v240, 7
	v_readlane_b32 s71, v240, 8
	s_mov_b64 s[30:31], -1
	s_waitcnt vmcnt(0)
	v_mov_b32_e32 v53, v56
	v_mov_b32_e32 v52, v54
	v_mov_b32_e32 v56, v55

.LBB0_2889:
	s_or_b64 exec, exec, s[0:1]
	s_mov_b32 s0, s70
	s_mov_b32 s1, s68
	s_waitcnt lgkmcnt(0)
	s_barrier
	v_mov_b32_e32 v0, v226
	s_ashr_i32 s2, s0, 3
	s_cmpk_gt_i32 s2, 0x9f
	v_readfirstlane_b32 s4, v0
	s_cbranch_scc1 .LBB0_2894
	s_ashr_i32 s3, s1, 3
	s_ashr_i32 s1, s4, 1
	v_bfe_u32 v1, v0, 2, 4
	s_andn2_b32 s1, s1, 31
	v_or_b32_e32 v83, s1, v1
	v_bfe_u32 v1, v0, 4, 2
	v_lshrrev_b32_e32 v2, 2, v0
	v_bitop3_b32 v2, v1, v2, 3 bitop3:0x78
	v_bitop3_b32 v4, v1, v0, 3 bitop3:0x78
	v_lshlrev_b32_e32 v3, 4, v2
	v_lshlrev_b32_e32 v2, 3, v4
	v_lshlrev_b32_e32 v68, 4, v4
	v_ashrrev_i32_e32 v4, 1, v0
	v_and_b32_e32 v82, 15, v0
	v_and_b32_e32 v84, 0xffffffc0, v4
	s_and_b32 s23, s0, 7
	v_or_b32_e32 v4, v84, v82
	v_and_b32_e32 v85, 64, v0
	v_lshlrev_b32_e32 v0, 6, v0
	s_movk_i32 s0, 0x13c0
	v_readlane_b32 s4, v241, 17
	v_readlane_b32 s44, v241, 1
	v_mov_b32_e32 v69, 0
	s_lshl_b32 s28, s1, 6
	v_lshl_or_b32 v86, v4, 6, v3
	v_and_or_b32 v3, v0, s0, v3
	v_lshlrev_b32_e32 v0, 2, v1
	v_readlane_b32 s5, v241, 18
	v_readlane_b32 s6, v241, 19
	v_readlane_b32 s7, v241, 20
	v_readlane_b32 s8, v241, 21
	v_readlane_b32 s9, v241, 22
	v_readlane_b32 s11, v241, 24
	v_readlane_b32 s54, v241, 11
	v_readlane_b32 s55, v241, 12
	s_mul_i32 s23, s23, 20
	v_lshl_add_u64 v[70:71], s[88:89], 0, v[68:69]
	s_movk_i32 s29, 0x2000
	v_or_b32_e32 v87, 0x2000, v3
	v_add_u32_e32 v88, 0x4000, v86
	s_movk_i32 s30, 0x6000
	v_or_b32_e32 v89, 0x6000, v3
	v_lshl_add_u64 v[72:73], s[8:9], 0, v[68:69]
	s_lshl_b32 s31, s2, 5
	s_lshl_b32 s33, s3, 5
	s_movk_i32 s34, 0x300
	s_mov_b64 s[0:1], 0x3000
	s_add_i32 s35, s28, 0x400
	s_add_i32 s36, s28, 0x2000
	s_mov_b64 s[4:5], 0x8000
	s_add_i32 s37, s28, 0x2400
	s_add_i32 s38, s28, 0x4000
	s_mov_b64 s[6:7], 0x3040
	s_add_i32 s39, s28, 0x4400
	s_add_i32 s40, s28, 0x6000
	s_mov_b64 s[8:9], 0x8040
	s_add_i32 s41, s28, 0x6400
	s_movk_i32 s42, 0x180
	s_mov_b32 s11, 0
	v_lshlrev_b32_e32 v68, 1, v2
	s_mov_b64 s[12:13], 0x80
	s_mov_b64 s[14:15], 0x8080
	s_mov_b64 s[16:17], 0xc0
	s_mov_b64 s[18:19], 0x80c0
	s_movk_i32 s43, 0xfff
	v_mov_b64_e32 v[74:75], s[54:55]
	v_lshlrev_b32_e32 v76, 2, v0
	v_mov_b32_e32 v77, v69
	s_mov_b64 s[20:21], 0x2000
	s_mov_b32 s22, 0x3fb504f3
	v_readlane_b32 s10, v241, 23
	v_readlane_b32 s45, v241, 2
	v_readlane_b32 s46, v241, 3
	v_readlane_b32 s47, v241, 4
	v_readlane_b32 s48, v241, 5
	v_readlane_b32 s49, v241, 6
	v_readlane_b32 s50, v241, 7
	v_readlane_b32 s51, v241, 8
	v_readlane_b32 s52, v241, 9
	v_readlane_b32 s53, v241, 10
	v_readlane_b32 s56, v241, 13
	v_readlane_b32 s57, v241, 14
	v_readlane_b32 s58, v241, 15
	v_readlane_b32 s59, v241, 16
	s_waitcnt vmcnt(0)
.LBB0_2891:
	s_ashr_i32 s10, s2, 31
	s_lshr_b32 s10, s10, 27
	s_add_i32 s10, s2, s10
	s_ashr_i32 s10, s10, 5
	s_lshl_b32 s24, s10, 2
	s_and_b32 s25, s2, 3
	s_add_i32 s24, s24, s23
	s_or_b32 s24, s24, s25
	s_lshl_b32 s44, s24, 7
	s_lshl_b32 s10, s10, 10
	s_lshl_b32 s24, s2, 5
	s_sub_i32 s24, s24, s10
	s_and_b32 s45, s24, 0xffffff80
	v_add_u32_e32 v64, s44, v83
	v_add_u32_e32 v0, s45, v83
	s_mov_b32 m0, s28
	v_ashrrev_i32_e32 v1, 31, v0
	v_mad_i64_i32 v[2:3], s[24:25], v64, s34, v[72:73]
	v_lshlrev_b64 v[0:1], 11, v[0:1]
	global_load_lds_dwordx4 v[2:3], off
	v_lshl_add_u64 v[4:5], v[2:3], 0, s[0:1]
	s_mov_b32 m0, s35
	v_lshl_add_u64 v[0:1], v[70:71], 0, v[0:1]
	global_load_lds_dwordx4 v[4:5], off
	s_mov_b32 m0, s36
	v_lshl_add_u64 v[4:5], v[0:1], 0, s[4:5]
	global_load_lds_dwordx4 v[0:1], off
	s_mov_b32 m0, s37
	s_sub_i32 s10, s31, s10
	global_load_lds_dwordx4 v[4:5], off
	v_lshl_add_u64 v[4:5], v[2:3], 0, 64
	s_mov_b32 m0, s38
	v_lshl_add_u64 v[2:3], v[2:3], 0, s[6:7]
	global_load_lds_dwordx4 v[4:5], off
	s_mov_b32 m0, s39
	s_and_b32 s10, s10, 0xffffff80
	global_load_lds_dwordx4 v[2:3], off
	v_lshl_add_u64 v[2:3], v[0:1], 0, 64
	s_mov_b32 m0, s40
	v_lshl_add_u64 v[0:1], v[0:1], 0, s[8:9]
	global_load_lds_dwordx4 v[2:3], off
	s_mov_b32 m0, s41
	v_readlane_b32 s52, v241, 17
	global_load_lds_dwordx4 v[0:1], off
	v_add_u32_e32 v0, s10, v83
	v_ashrrev_i32_e32 v1, 31, v0
	v_lshlrev_b64 v[0:1], 11, v[0:1]
	v_lshl_add_u64 v[66:67], v[70:71], 0, v[0:1]
	s_mov_b64 s[24:25], 0
	s_mov_b64 s[26:27], 0
	s_mov_b32 s46, s11
	s_mov_b32 s47, 2
	s_mov_b32 s48, s11
	v_mov_b32_e32 v24, 0
	v_mov_b32_e32 v25, v69
	v_mov_b32_e32 v26, v69
	v_mov_b32_e32 v27, v69
	v_mov_b32_e32 v0, 0
	v_mov_b32_e32 v1, v69
	v_mov_b32_e32 v2, v69
	v_mov_b32_e32 v3, v69
	v_mov_b32_e32 v4, 0
	v_mov_b32_e32 v5, v69
	v_mov_b32_e32 v6, v69
	v_mov_b32_e32 v7, v69
	v_mov_b32_e32 v8, 0
	v_mov_b32_e32 v9, v69
	v_mov_b32_e32 v10, v69
	v_mov_b32_e32 v11, v69
	v_mov_b32_e32 v12, 0
	v_mov_b32_e32 v13, v69
	v_mov_b32_e32 v14, v69
	v_mov_b32_e32 v15, v69
	v_mov_b32_e32 v16, 0
	v_mov_b32_e32 v17, v69
	v_mov_b32_e32 v18, v69
	v_mov_b32_e32 v19, v69
	v_mov_b32_e32 v20, 0
	v_mov_b32_e32 v21, v69
	v_mov_b32_e32 v22, v69
	v_mov_b32_e32 v23, v69
	v_mov_b32_e32 v28, 0
	v_mov_b32_e32 v29, v69
	v_mov_b32_e32 v30, v69
	v_mov_b32_e32 v31, v69
	v_mov_b32_e32 v32, 0
	v_mov_b32_e32 v33, v69
	v_mov_b32_e32 v34, v69
	v_mov_b32_e32 v35, v69
	v_mov_b32_e32 v36, 0
	v_mov_b32_e32 v37, v69
	v_mov_b32_e32 v38, v69
	v_mov_b32_e32 v39, v69
	v_mov_b32_e32 v40, 0
	v_mov_b32_e32 v41, v69
	v_mov_b32_e32 v42, v69
	v_mov_b32_e32 v43, v69
	v_mov_b32_e32 v44, 0
	v_mov_b32_e32 v45, v69
	v_mov_b32_e32 v46, v69
	v_mov_b32_e32 v47, v69
	v_mov_b32_e32 v48, 0
	v_mov_b32_e32 v49, v69
	v_mov_b32_e32 v50, v69
	v_mov_b32_e32 v51, v69
	v_mov_b32_e32 v52, 0
	v_mov_b32_e32 v53, v69
	v_mov_b32_e32 v54, v69
	v_mov_b32_e32 v55, v69
	v_mov_b32_e32 v56, 0
	v_mov_b32_e32 v57, v69
	v_mov_b32_e32 v58, v69
	v_mov_b32_e32 v59, v69
	v_mov_b32_e32 v60, 0
	v_mov_b32_e32 v61, v69
	v_mov_b32_e32 v62, v69
	v_mov_b32_e32 v63, v69
	v_readlane_b32 s56, v241, 21
	v_readlane_b32 s57, v241, 22
	v_readlane_b32 s58, v241, 23
	v_readlane_b32 s59, v241, 24
	v_readlane_b32 s53, v241, 18
	v_readlane_b32 s54, v241, 19
	v_readlane_b32 s55, v241, 20

.LBB0_3003:
	s_or_b64 exec, exec, s[0:1]
	s_mov_b32 s3, s68
	s_mov_b32 s0, s70
	s_waitcnt lgkmcnt(0)
	s_barrier
	v_mov_b32_e32 v0, v226
	s_ashr_i32 s2, s0, 3
	s_cmpk_gt_i32 s2, 0x1b7
	v_readfirstlane_b32 s1, v0
	s_cbranch_scc1 .LBB0_3008
	v_bfe_u32 v1, v0, 4, 2
	v_lshrrev_b32_e32 v2, 2, v0
	v_bitop3_b32 v2, v1, v2, 3 bitop3:0x78
	v_lshlrev_b32_e32 v2, 3, v2
	v_lshlrev_b32_e32 v3, 5, v0
	s_mov_b32 s4, 0x7ffff1e0
	v_and_or_b32 v4, v3, s4, v2
	s_movk_i32 s4, 0x9e0
	s_waitcnt vmcnt(0)
	v_lshlrev_b32_e32 v139, 1, v4
	v_and_or_b32 v2, v3, s4, v2
	s_ashr_i32 s4, s1, 6
	v_bfe_u32 v4, v0, 2, 4
	s_andn2_b32 s1, s1, 63
	s_ashr_i32 s3, s3, 3
	v_or_b32_e32 v142, s1, v4
	s_lshl_b32 s1, s4, 11
	s_and_b32 s28, s0, 7
	s_lshl_b32 s29, s4, 12
	s_sub_i32 s30, 0, s1
	s_lshl_b32 s31, s2, 6
	s_lshl_b32 s33, s3, 6
	v_bitop3_b32 v3, v1, v0, 3 bitop3:0x78
	v_lshlrev_b32_e32 v1, 2, v1
	s_movk_i32 s1, 0xff80
	s_bitcmp1_b32 s0, 3
	v_and_or_b32 v145, v0, s1, v1
	s_cselect_b64 s[0:1], -1, 0
	s_bitcmp1_b32 s3, 0
	v_lshlrev_b32_e32 v2, 1, v2
	v_lshlrev_b32_e32 v128, 4, v3
	v_mov_b32_e32 v129, 0
	v_lshl_or_b32 v143, s4, 5, v4
	s_cselect_b64 s[4:5], -1, 0
	s_add_i32 s44, s29, s30
	v_readlane_b32 s52, v241, 17
	v_and_b32_e32 v138, 15, v0
	v_and_b32_e32 v140, 64, v0
	v_or_b32_e32 v141, 0x4000, v2
	s_mul_i32 s28, s28, 10
	v_lshl_add_u64 v[130:131], s[78:79], 0, v[128:129]
	v_lshl_add_u64 v[132:133], s[90:91], 0, v[128:129]
	v_add_u32_e32 v128, 0x6000, v139
	v_or_b32_e32 v144, 0xa000, v2
	s_mov_b64 s[6:7], 0x8000
	s_add_i32 s34, s29, 0x400
	s_mov_b64 s[8:9], 0x10000
	s_add_i32 s35, s29, 0x800
	s_mov_b64 s[10:11], 0x18000
	s_add_i32 s36, s29, 0xc00
	s_add_i32 s37, s44, 0x4000
	s_add_i32 s38, s44, 0x4400
	s_add_i32 s39, s29, 0x6000
	s_mov_b64 s[12:13], 0x8040
	s_add_i32 s40, s29, 0x6400
	s_mov_b64 s[14:15], 0x10040
	s_add_i32 s41, s29, 0x6800
	s_mov_b64 s[16:17], 0x18040
	s_add_i32 s42, s29, 0x6c00
	s_add_i32 s43, s44, 0xa000
	s_add_i32 s44, s44, 0xa400
	s_movk_i32 s45, 0x1600
	s_mov_b64 s[18:19], 0x80
	s_mov_b64 s[20:21], 0x8080
	s_mov_b64 s[22:23], 0x10080
	s_mov_b64 s[24:25], 0x18080
	s_movk_i32 s46, 0x7fff
	v_readlane_b32 s53, v241, 18
	v_readlane_b32 s54, v241, 19
	v_readlane_b32 s55, v241, 20
	v_readlane_b32 s56, v241, 21
	v_readlane_b32 s57, v241, 22
	v_readlane_b32 s58, v241, 23
	v_readlane_b32 s59, v241, 24
	s_waitcnt vmcnt(0)
.LBB0_3005:
	s_mul_hi_i32 s26, s2, 0x2e8ba2e9
	s_lshr_b32 s27, s26, 31
	s_ashr_i32 s26, s26, 4
	s_add_i32 s26, s26, s27
	s_lshl_b32 s48, s26, 1
	s_and_b32 s47, s2, 1
	s_add_i32 s49, s48, s28
	s_or_b32 s47, s49, s47
	s_lshl_b32 s47, s47, 8
	s_mul_i32 s27, s26, 0xffffffa8
	v_add_u32_e32 v0, s47, v142
	s_add_i32 s27, s27, s2
	v_ashrrev_i32_e32 v1, 31, v0
	v_lshlrev_b64 v[0:1], 11, v[0:1]
	s_lshl_b32 s27, s27, 6
	s_mov_b32 m0, s29
	v_lshl_add_u64 v[0:1], v[130:131], 0, v[0:1]
	s_and_b32 s48, s27, 0xffffff80
	v_add_u32_e32 v2, s48, v143
	global_load_lds_dwordx4 v[0:1], off
	v_lshl_add_u64 v[4:5], v[0:1], 0, s[6:7]
	s_mov_b32 m0, s34
	v_ashrrev_i32_e32 v3, 31, v2
	global_load_lds_dwordx4 v[4:5], off
	v_lshl_add_u64 v[4:5], v[0:1], 0, s[8:9]
	s_mov_b32 m0, s35
	v_lshlrev_b64 v[2:3], 11, v[2:3]
	global_load_lds_dwordx4 v[4:5], off
	v_lshl_add_u64 v[4:5], v[0:1], 0, s[10:11]
	s_mov_b32 m0, s36
	v_lshl_add_u64 v[2:3], v[132:133], 0, v[2:3]
	global_load_lds_dwordx4 v[4:5], off
	s_mov_b32 m0, s37
	v_lshl_add_u64 v[4:5], v[2:3], 0, s[6:7]
	global_load_lds_dwordx4 v[2:3], off
	s_mov_b32 m0, s38
	s_mulk_i32 s26, 0x1600
	global_load_lds_dwordx4 v[4:5], off
	v_lshl_add_u64 v[4:5], v[0:1], 0, 64
	s_mov_b32 m0, s39
	s_sub_i32 s26, s31, s26
	global_load_lds_dwordx4 v[4:5], off
	v_lshl_add_u64 v[4:5], v[0:1], 0, s[12:13]
	s_mov_b32 m0, s40
	s_and_b32 s26, s26, 0xffffff80
	global_load_lds_dwordx4 v[4:5], off
	v_lshl_add_u64 v[4:5], v[0:1], 0, s[14:15]
	s_mov_b32 m0, s41
	v_lshl_add_u64 v[0:1], v[0:1], 0, s[16:17]
	global_load_lds_dwordx4 v[4:5], off
	s_mov_b32 m0, s42
	v_cndmask_b32_e64 v6, 0, 1, s[0:1]
	global_load_lds_dwordx4 v[0:1], off
	v_lshl_add_u64 v[0:1], v[2:3], 0, 64
	s_mov_b32 m0, s43
	s_mov_b32 s50, 0
	global_load_lds_dwordx4 v[0:1], off
	v_lshl_add_u64 v[0:1], v[2:3], 0, s[12:13]
	s_mov_b32 m0, s44
	v_mov_b32_e32 v2, v129
	global_load_lds_dwordx4 v[0:1], off
	v_add_u32_e32 v0, s26, v143
	v_ashrrev_i32_e32 v1, 31, v0
	v_lshlrev_b64 v[0:1], 11, v[0:1]
	v_lshl_add_u64 v[134:135], v[132:133], 0, v[0:1]
	v_add_u32_e32 v0, s49, v6
	v_lshl_add_u32 v0, v0, 8, v142
	v_ashrrev_i32_e32 v1, 31, v0
	v_lshlrev_b64 v[0:1], 11, v[0:1]
	v_lshl_add_u64 v[136:137], v[130:131], 0, v[0:1]
	s_mov_b64 s[26:27], 0
	s_mov_b32 s49, 2
	v_mov_b32_e32 v0, 0
	v_mov_b32_e32 v1, v129
	v_mov_b32_e32 v3, v129
	v_mov_b32_e32 v4, 0
	v_mov_b32_e32 v5, v129
	v_mov_b32_e32 v6, v129
	v_mov_b32_e32 v7, v129
	v_mov_b32_e32 v8, 0
	v_mov_b32_e32 v9, v129
	v_mov_b32_e32 v10, v129
	v_mov_b32_e32 v11, v129
	v_mov_b32_e32 v12, 0
	v_mov_b32_e32 v13, v129
	v_mov_b32_e32 v14, v129
	v_mov_b32_e32 v15, v129
	v_mov_b32_e32 v16, 0
	v_mov_b32_e32 v17, v129
	v_mov_b32_e32 v18, v129
	v_mov_b32_e32 v19, v129
	v_mov_b32_e32 v20, 0
	v_mov_b32_e32 v21, v129
	v_mov_b32_e32 v22, v129
	v_mov_b32_e32 v23, v129
	v_mov_b32_e32 v24, 0
	v_mov_b32_e32 v25, v129
	v_mov_b32_e32 v26, v129
	v_mov_b32_e32 v27, v129
	v_mov_b32_e32 v28, 0
	v_mov_b32_e32 v29, v129
	v_mov_b32_e32 v30, v129
	v_mov_b32_e32 v31, v129
	v_mov_b32_e32 v32, 0
	v_mov_b32_e32 v33, v129
	v_mov_b32_e32 v34, v129
	v_mov_b32_e32 v35, v129
	v_mov_b32_e32 v36, 0
	v_mov_b32_e32 v37, v129
	v_mov_b32_e32 v38, v129
	v_mov_b32_e32 v39, v129
	v_mov_b32_e32 v44, 0
	v_mov_b32_e32 v45, v129
	v_mov_b32_e32 v46, v129
	v_mov_b32_e32 v47, v129
	v_mov_b32_e32 v52, 0
	v_mov_b32_e32 v53, v129
	v_mov_b32_e32 v54, v129
	v_mov_b32_e32 v55, v129
	v_mov_b32_e32 v60, 0
	v_mov_b32_e32 v61, v129
	v_mov_b32_e32 v62, v129
	v_mov_b32_e32 v63, v129
	v_mov_b32_e32 v68, 0
	v_mov_b32_e32 v69, v129
	v_mov_b32_e32 v70, v129
	v_mov_b32_e32 v71, v129
	v_mov_b32_e32 v76, 0
	v_mov_b32_e32 v77, v129
	v_mov_b32_e32 v78, v129
	v_mov_b32_e32 v79, v129
	v_mov_b32_e32 v84, 0
	v_mov_b32_e32 v85, v129
	v_mov_b32_e32 v86, v129
	v_mov_b32_e32 v87, v129
	v_mov_b32_e32 v40, 0
	v_mov_b32_e32 v41, v129
	v_mov_b32_e32 v42, v129
	v_mov_b32_e32 v43, v129
	v_mov_b32_e32 v48, 0
	v_mov_b32_e32 v49, v129
	v_mov_b32_e32 v50, v129
	v_mov_b32_e32 v51, v129
	v_mov_b32_e32 v56, 0
	v_mov_b32_e32 v57, v129
	v_mov_b32_e32 v58, v129
	v_mov_b32_e32 v59, v129
	v_mov_b32_e32 v64, 0
	v_mov_b32_e32 v65, v129
	v_mov_b32_e32 v66, v129
	v_mov_b32_e32 v67, v129
	v_mov_b32_e32 v72, 0
	v_mov_b32_e32 v73, v129
	v_mov_b32_e32 v74, v129
	v_mov_b32_e32 v75, v129
	v_mov_b32_e32 v80, 0
	v_mov_b32_e32 v81, v129
	v_mov_b32_e32 v82, v129
	v_mov_b32_e32 v83, v129
	v_mov_b32_e32 v88, 0
	v_mov_b32_e32 v89, v129
	v_mov_b32_e32 v90, v129
	v_mov_b32_e32 v91, v129
	v_mov_b32_e32 v92, 0
	v_mov_b32_e32 v93, v129
	v_mov_b32_e32 v94, v129
	v_mov_b32_e32 v95, v129
	v_mov_b32_e32 v96, 0
	v_mov_b32_e32 v97, v129
	v_mov_b32_e32 v98, v129
	v_mov_b32_e32 v99, v129
	v_mov_b32_e32 v100, 0
	v_mov_b32_e32 v101, v129
	v_mov_b32_e32 v102, v129
	v_mov_b32_e32 v103, v129
	v_mov_b32_e32 v104, 0
	v_mov_b32_e32 v105, v129
	v_mov_b32_e32 v106, v129
	v_mov_b32_e32 v107, v129
	v_mov_b32_e32 v108, 0
	v_mov_b32_e32 v109, v129
	v_mov_b32_e32 v110, v129
	v_mov_b32_e32 v111, v129
	v_mov_b32_e32 v112, 0
	v_mov_b32_e32 v113, v129
	v_mov_b32_e32 v114, v129
	v_mov_b32_e32 v115, v129
	v_mov_b32_e32 v116, 0
	v_mov_b32_e32 v117, v129
	v_mov_b32_e32 v118, v129
	v_mov_b32_e32 v119, v129
	v_mov_b32_e32 v120, 0
	v_mov_b32_e32 v121, v129
	v_mov_b32_e32 v122, v129
	v_mov_b32_e32 v123, v129
	v_mov_b32_e32 v124, 0
	v_mov_b32_e32 v125, v129
	v_mov_b32_e32 v126, v129
	v_mov_b32_e32 v127, v129

.LBB0_3060:
	s_or_b64 exec, exec, s[0:1]
	s_mov_b32 s0, s70
	s_mov_b32 s14, s68
	s_waitcnt lgkmcnt(0)
	s_barrier
	v_mov_b32_e32 v0, v226
	s_ashr_i32 s2, s0, 3
	s_cmpk_gt_i32 s2, 0x9f
	v_readfirstlane_b32 s1, v0
	s_cbranch_scc1 .LBB0_3065
	s_ashr_i32 s1, s1, 1
	v_bfe_u32 v1, v0, 2, 4
	s_andn2_b32 s1, s1, 31
	v_or_b32_e32 v77, s1, v1
	v_bfe_u32 v1, v0, 4, 2
	v_bitop3_b32 v3, v1, v0, 3 bitop3:0x78
	v_lshrrev_b32_e32 v2, 2, v0
	v_lshlrev_b32_e32 v64, 4, v3
	v_ashrrev_i32_e32 v3, 1, v0
	v_and_b32_e32 v76, 15, v0
	v_bitop3_b32 v2, v1, v2, 3 bitop3:0x78
	v_and_b32_e32 v78, 0xffffffc0, v3
	s_lshr_b32 s17, s0, 3
	v_lshlrev_b32_e32 v2, 4, v2
	s_and_b32 s20, s0, 7
	v_or_b32_e32 v3, v78, v76
	v_and_b32_e32 v79, 64, v0
	v_lshlrev_b32_e32 v0, 6, v0
	s_movk_i32 s0, 0x13c0
	v_readlane_b32 s36, v241, 1
	s_ashr_i32 s3, s14, 3
	v_mov_b32_e32 v65, 0
	s_lshl_b32 s21, s1, 6
	v_lshl_or_b32 v80, v3, 6, v2
	v_and_or_b32 v2, v0, s0, v2
	v_lshlrev_b32_e32 v0, 2, v1
	v_readlane_b32 s46, v241, 11
	v_readlane_b32 s47, v241, 12
	s_mul_i32 s20, s20, 20
	v_lshl_add_u64 v[66:67], s[92:93], 0, v[64:65]
	v_or_b32_e32 v81, 0x2000, v2
	v_add_u32_e32 v82, 0x8000, v80
	v_or_b32_e32 v83, 0xa000, v2
	v_lshl_add_u64 v[68:69], s[24:25], 0, v[64:65]
	s_lshl_b32 s22, s2, 5
	s_lshl_b32 s23, s3, 5
	s_movk_i32 s24, 0x1600
	s_mov_b64 s[0:1], 0x16000
	s_add_i32 s25, s21, 0x400
	s_add_i32 s26, s21, 0x2000
	s_add_i32 s27, s21, 0x2400
	s_add_i32 s28, s21, 0x4000
	s_mov_b64 s[4:5], 0x16040
	s_add_i32 s29, s21, 0x4400
	s_movk_i32 s30, 0x6000
	s_add_i32 s31, s21, 0x6000
	s_add_i32 s33, s21, 0x6400
	s_mov_b64 s[6:7], 0x80
	s_mov_b64 s[8:9], 0x16080
	s_mov_b64 s[10:11], 0xc0
	s_mov_b64 s[12:13], 0x160c0
	s_lshr_b32 s34, s14, 3
	s_movk_i32 s35, 0xfff
	v_mov_b64_e32 v[70:71], s[46:47]
	v_lshlrev_b32_e32 v64, 2, v0
	s_mov_b64 s[14:15], 0x5000
	s_movk_i32 s36, 0x5000
	s_mov_b32 s16, 0x3fb504f3
	v_readlane_b32 s37, v241, 2
	v_readlane_b32 s38, v241, 3
	v_readlane_b32 s39, v241, 4
	v_readlane_b32 s40, v241, 5
	v_readlane_b32 s41, v241, 6
	v_readlane_b32 s42, v241, 7
	v_readlane_b32 s43, v241, 8
	v_readlane_b32 s44, v241, 9
	v_readlane_b32 s45, v241, 10
	v_readlane_b32 s48, v241, 13
	v_readlane_b32 s49, v241, 14
	v_readlane_b32 s50, v241, 15
	v_readlane_b32 s51, v241, 16
	s_waitcnt vmcnt(0)
.LBB0_3062:
	s_ashr_i32 s18, s2, 31
	s_lshr_b32 s18, s18, 27
	s_add_i32 s18, s2, s18
	s_ashr_i32 s18, s18, 5
	s_lshl_b32 s19, s18, 2
	s_and_b32 s37, s2, 3
	s_add_i32 s39, s19, s20
	s_or_b32 s19, s39, s37
	s_lshl_b32 s37, s19, 7
	s_lshl_b32 s40, s18, 10
	s_lshl_b32 s18, s2, 5
	v_add_u32_e32 v2, s37, v77
	s_sub_i32 s18, s18, s40
	s_mov_b32 m0, s21
	s_and_b32 s38, s18, 0xffffff80
	v_mad_i64_i32 v[2:3], s[18:19], v2, s24, v[68:69]
	v_add_u32_e32 v0, s38, v77
	global_load_lds_dwordx4 v[2:3], off
	v_lshl_add_u64 v[4:5], v[2:3], 0, s[0:1]
	s_mov_b32 m0, s25
	v_mad_i64_i32 v[0:1], s[18:19], v0, s24, v[66:67]
	global_load_lds_dwordx4 v[4:5], off
	s_mov_b32 m0, s26
	v_lshl_add_u64 v[4:5], v[0:1], 0, s[0:1]
	global_load_lds_dwordx4 v[0:1], off
	s_mov_b32 m0, s27
	s_sub_i32 s18, s22, s40
	global_load_lds_dwordx4 v[4:5], off
	v_lshl_add_u64 v[4:5], v[2:3], 0, 64
	s_mov_b32 m0, s28
	v_lshl_add_u64 v[2:3], v[2:3], 0, s[4:5]
	global_load_lds_dwordx4 v[4:5], off
	s_mov_b32 m0, s29
	s_and_b32 s41, s17, 3
	global_load_lds_dwordx4 v[2:3], off
	v_lshl_add_u64 v[2:3], v[0:1], 0, 64
	s_mov_b32 m0, s31
	v_lshl_add_u64 v[0:1], v[0:1], 0, s[4:5]
	global_load_lds_dwordx4 v[2:3], off
	s_mov_b32 m0, s33
	s_and_b32 s18, s18, 0xffffff80
	global_load_lds_dwordx4 v[0:1], off
	v_add_u32_e32 v0, s18, v77
	s_add_i32 s39, s39, s41
	v_mad_i64_i32 v[72:73], s[18:19], v0, s24, v[66:67]
	v_lshl_add_u32 v0, s39, 7, v77
	v_mad_i64_i32 v[74:75], s[18:19], v0, s24, v[68:69]
	s_mov_b64 s[18:19], 0
	s_mov_b32 s39, 2
	s_mov_b32 s40, 0
	v_mov_b32_e32 v20, 0
	v_mov_b32_e32 v21, v65
	v_mov_b32_e32 v22, v65
	v_mov_b32_e32 v23, v65
	v_mov_b32_e32 v0, 0
	v_mov_b32_e32 v1, v65
	v_mov_b32_e32 v2, v65
	v_mov_b32_e32 v3, v65
	v_mov_b32_e32 v4, 0
	v_mov_b32_e32 v5, v65
	v_mov_b32_e32 v6, v65
	v_mov_b32_e32 v7, v65
	v_mov_b32_e32 v8, 0
	v_mov_b32_e32 v9, v65
	v_mov_b32_e32 v10, v65
	v_mov_b32_e32 v11, v65
	v_mov_b32_e32 v12, 0
	v_mov_b32_e32 v13, v65
	v_mov_b32_e32 v14, v65
	v_mov_b32_e32 v15, v65
	v_mov_b32_e32 v16, 0
	v_mov_b32_e32 v17, v65
	v_mov_b32_e32 v18, v65
	v_mov_b32_e32 v19, v65
	v_mov_b32_e32 v24, 0
	v_mov_b32_e32 v25, v65
	v_mov_b32_e32 v26, v65
	v_mov_b32_e32 v27, v65
	v_mov_b32_e32 v28, 0
	v_mov_b32_e32 v29, v65
	v_mov_b32_e32 v30, v65
	v_mov_b32_e32 v31, v65
	v_mov_b32_e32 v32, 0
	v_mov_b32_e32 v33, v65
	v_mov_b32_e32 v34, v65
	v_mov_b32_e32 v35, v65
	v_mov_b32_e32 v36, 0
	v_mov_b32_e32 v37, v65
	v_mov_b32_e32 v38, v65
	v_mov_b32_e32 v39, v65
	v_mov_b32_e32 v40, 0
	v_mov_b32_e32 v41, v65
	v_mov_b32_e32 v42, v65
	v_mov_b32_e32 v43, v65
	v_mov_b32_e32 v44, 0
	v_mov_b32_e32 v45, v65
	v_mov_b32_e32 v46, v65
	v_mov_b32_e32 v47, v65
	v_mov_b32_e32 v48, 0
	v_mov_b32_e32 v49, v65
	v_mov_b32_e32 v50, v65
	v_mov_b32_e32 v51, v65
	v_mov_b32_e32 v52, 0
	v_mov_b32_e32 v53, v65
	v_mov_b32_e32 v54, v65
	v_mov_b32_e32 v55, v65
	v_mov_b32_e32 v56, 0
	v_mov_b32_e32 v57, v65
	v_mov_b32_e32 v58, v65
	v_mov_b32_e32 v59, v65
	v_mov_b32_e32 v60, 0
	v_mov_b32_e32 v61, v65
	v_mov_b32_e32 v62, v65
	v_mov_b32_e32 v63, v65
